# GEMM K loops: 6 of 16 LDS-DMA loads per iteration use the scalar-base form (global_load_lds v_off, s[ptr]) instead of a 64-bit VALU address add
# baseline (speedup 1.0000x reference)
.LBB0_118:
	ds_read_b128 v[128:131], v221
	ds_read_b128 v[132:135], v221 offset:1024
	ds_read_b128 v[136:139], v221 offset:2048
	ds_read_b128 v[140:143], v221 offset:3072
	s_add_u32 s8, s6, 0xfff80080
	s_addc_u32 s9, s7, -1
	s_cmp_eq_u32 s53, 28
	s_cselect_b32 s11, s5, s9
	s_cselect_b32 s10, s33, s8
	s_cselect_b32 s9, s43, s52
	s_cselect_b32 s8, s45, s51
	v_lshl_add_u64 v[198:199], s[6:7], 0, v[182:183]
	s_add_i32 m0, s58, 0xc000
	ds_read_b128 v[144:147], v222
	ds_read_b128 v[148:151], v222 offset:1024
	ds_read_b128 v[152:155], v222 offset:2048
	ds_read_b128 v[156:159], v222 offset:3072
	ds_read_b128 v[160:163], v222 offset:4096
	ds_read_b128 v[164:167], v222 offset:5120
	ds_read_b128 v[190:193], v222 offset:6144
	ds_read_b128 v[194:197], v222 offset:7168
	global_load_lds_dwordx4 v[198:199], off
	s_add_i32 m0, s58, 0xe000
	s_nop 0

	global_load_lds_dwordx4 v184, s[6:7]
	s_waitcnt lgkmcnt(8)
	s_barrier
	s_waitcnt lgkmcnt(0)


	v_mfma_f32_16x16x32_bf16 v[124:127], v[128:131], v[144:147], v[124:127]
	v_mfma_f32_16x16x32_bf16 v[116:119], v[136:139], v[144:147], v[116:119]
	v_mfma_f32_16x16x32_bf16 v[108:111], v[128:131], v[152:155], v[108:111]
	v_mfma_f32_16x16x32_bf16 v[100:103], v[136:139], v[152:155], v[100:103]
	v_mfma_f32_16x16x32_bf16 v[92:95], v[128:131], v[160:163], v[92:95]
	v_mfma_f32_16x16x32_bf16 v[84:87], v[136:139], v[160:163], v[84:87]
	v_mfma_f32_16x16x32_bf16 v[76:79], v[128:131], v[190:193], v[76:79]
	v_mfma_f32_16x16x32_bf16 v[68:71], v[136:139], v[190:193], v[68:71]
	v_mfma_f32_16x16x32_bf16 v[124:127], v[132:135], v[148:151], v[124:127]
	v_mfma_f32_16x16x32_bf16 v[116:119], v[140:143], v[148:151], v[116:119]
	v_mfma_f32_16x16x32_bf16 v[108:111], v[132:135], v[156:159], v[108:111]
	v_mfma_f32_16x16x32_bf16 v[100:103], v[140:143], v[156:159], v[100:103]
	v_mfma_f32_16x16x32_bf16 v[92:95], v[132:135], v[164:167], v[92:95]
	v_mfma_f32_16x16x32_bf16 v[84:87], v[140:143], v[164:167], v[84:87]
	v_mfma_f32_16x16x32_bf16 v[76:79], v[132:135], v[194:197], v[76:79]
	v_mfma_f32_16x16x32_bf16 v[68:71], v[140:143], v[194:197], v[68:71]

	s_barrier
	s_add_i32 s54, s81, s57
	v_lshl_add_u64 v[230:231], s[8:9], 0, v[172:173]
	s_mov_b32 m0, s54
	ds_read_b128 v[198:201], v223
	ds_read_b128 v[202:205], v223 offset:1024
	ds_read_b128 v[206:209], v223 offset:2048
	ds_read_b128 v[226:229], v223 offset:3072
	global_load_lds_dwordx4 v[230:231], off
	s_add_i32 m0, s54, 0x2000
	v_lshl_add_u64 v[232:233], s[8:9], 0, v[174:175]

	global_load_lds_dwordx4 v[232:233], off
	s_barrier
	s_waitcnt lgkmcnt(0)


	v_mfma_f32_16x16x32_bf16 v[120:123], v[198:201], v[144:147], v[120:123]
	v_mfma_f32_16x16x32_bf16 v[112:115], v[206:209], v[144:147], v[112:115]
	v_mfma_f32_16x16x32_bf16 v[104:107], v[198:201], v[152:155], v[104:107]
	v_mfma_f32_16x16x32_bf16 v[96:99], v[206:209], v[152:155], v[96:99]
	v_mfma_f32_16x16x32_bf16 v[88:91], v[198:201], v[160:163], v[88:91]
	v_mfma_f32_16x16x32_bf16 v[80:83], v[206:209], v[160:163], v[80:83]
	v_mfma_f32_16x16x32_bf16 v[72:75], v[198:201], v[190:193], v[72:75]
	v_mfma_f32_16x16x32_bf16 v[64:67], v[206:209], v[190:193], v[64:67]
	v_mfma_f32_16x16x32_bf16 v[120:123], v[202:205], v[148:151], v[120:123]
	v_mfma_f32_16x16x32_bf16 v[112:115], v[226:229], v[148:151], v[112:115]
	v_mfma_f32_16x16x32_bf16 v[104:107], v[202:205], v[156:159], v[104:107]
	v_mfma_f32_16x16x32_bf16 v[96:99], v[226:229], v[156:159], v[96:99]
	v_mfma_f32_16x16x32_bf16 v[88:91], v[202:205], v[164:167], v[88:91]
	v_mfma_f32_16x16x32_bf16 v[80:83], v[226:229], v[164:167], v[80:83]
	v_mfma_f32_16x16x32_bf16 v[72:75], v[202:205], v[194:197], v[72:75]
	v_mfma_f32_16x16x32_bf16 v[64:67], v[226:229], v[194:197], v[64:67]

	s_mov_b32 m0, s58
	v_lshl_add_u64 v[234:235], s[10:11], 0, v[172:173]
	s_barrier
	ds_read_b128 v[144:147], v222 offset:16384
	ds_read_b128 v[148:151], v222 offset:17408
	ds_read_b128 v[152:155], v222 offset:18432
	ds_read_b128 v[156:159], v222 offset:19456
	ds_read_b128 v[160:163], v222 offset:20480
	ds_read_b128 v[164:167], v222 offset:21504
	ds_read_b128 v[190:193], v222 offset:22528
	ds_read_b128 v[194:197], v222 offset:23552
	global_load_lds_dwordx4 v[234:235], off
	s_mov_b32 m0, s59
	v_lshl_add_u64 v[236:237], s[10:11], 0, v[174:175]

	global_load_lds_dwordx4 v[236:237], off
	s_barrier
	s_waitcnt lgkmcnt(0)


	v_mfma_f32_16x16x32_bf16 v[60:63], v[128:131], v[144:147], v[60:63]
	v_mfma_f32_16x16x32_bf16 v[52:55], v[136:139], v[144:147], v[52:55]
	v_mfma_f32_16x16x32_bf16 v[44:47], v[128:131], v[152:155], v[44:47]
	v_mfma_f32_16x16x32_bf16 v[36:39], v[136:139], v[152:155], v[36:39]
	v_mfma_f32_16x16x32_bf16 v[28:31], v[128:131], v[160:163], v[28:31]
	v_mfma_f32_16x16x32_bf16 v[20:23], v[136:139], v[160:163], v[20:23]
	v_mfma_f32_16x16x32_bf16 v[12:15], v[128:131], v[190:193], v[12:15]
	v_mfma_f32_16x16x32_bf16 v[4:7], v[136:139], v[190:193], v[4:7]
	v_mfma_f32_16x16x32_bf16 v[60:63], v[132:135], v[148:151], v[60:63]
	v_mfma_f32_16x16x32_bf16 v[52:55], v[140:143], v[148:151], v[52:55]
	v_mfma_f32_16x16x32_bf16 v[44:47], v[132:135], v[156:159], v[44:47]
	v_mfma_f32_16x16x32_bf16 v[36:39], v[140:143], v[156:159], v[36:39]
	v_mfma_f32_16x16x32_bf16 v[28:31], v[132:135], v[164:167], v[28:31]
	v_mfma_f32_16x16x32_bf16 v[20:23], v[140:143], v[164:167], v[20:23]
	v_mfma_f32_16x16x32_bf16 v[12:15], v[132:135], v[194:197], v[12:15]
	v_mfma_f32_16x16x32_bf16 v[4:7], v[140:143], v[194:197], v[4:7]

	s_barrier
	s_add_u32 s54, s8, 0x80000
	s_addc_u32 s55, s9, 0
	s_add_i32 vcc_lo, s30, s57
	s_mov_b32 m0, vcc_lo
	s_nop 0

	global_load_lds_dwordx4 v172, s[54:55]
	s_add_i32 m0, vcc_lo, 0x2000
	s_nop 0

	global_load_lds_dwordx4 v174, s[54:55]
	s_waitcnt vmcnt(6)
	s_barrier

	v_mfma_f32_16x16x32_bf16 v[56:59], v[198:201], v[144:147], v[56:59]
	v_mfma_f32_16x16x32_bf16 v[48:51], v[206:209], v[144:147], v[48:51]
	v_mfma_f32_16x16x32_bf16 v[40:43], v[198:201], v[152:155], v[40:43]
	v_mfma_f32_16x16x32_bf16 v[32:35], v[206:209], v[152:155], v[32:35]
	v_mfma_f32_16x16x32_bf16 v[24:27], v[198:201], v[160:163], v[24:27]
	v_mfma_f32_16x16x32_bf16 v[16:19], v[206:209], v[160:163], v[16:19]
	v_mfma_f32_16x16x32_bf16 v[8:11], v[198:201], v[190:193], v[8:11]
	v_mfma_f32_16x16x32_bf16 v[0:3], v[206:209], v[190:193], v[0:3]
	v_mfma_f32_16x16x32_bf16 v[56:59], v[202:205], v[148:151], v[56:59]
	v_mfma_f32_16x16x32_bf16 v[48:51], v[226:229], v[148:151], v[48:51]
	v_mfma_f32_16x16x32_bf16 v[40:43], v[202:205], v[156:159], v[40:43]
	v_mfma_f32_16x16x32_bf16 v[32:35], v[226:229], v[156:159], v[32:35]
	v_mfma_f32_16x16x32_bf16 v[24:27], v[202:205], v[164:167], v[24:27]
	v_mfma_f32_16x16x32_bf16 v[16:19], v[226:229], v[164:167], v[16:19]
	v_mfma_f32_16x16x32_bf16 v[8:11], v[202:205], v[194:197], v[8:11]
	v_mfma_f32_16x16x32_bf16 v[0:3], v[226:229], v[194:197], v[0:3]

	s_add_i32 s54, 0, 0x18000
	v_add_u32_e32 v140, s54, v179
	s_barrier
	ds_read_b128 v[128:131], v140
	ds_read_b128 v[132:135], v140 offset:1024
	ds_read_b128 v[136:139], v140 offset:2048
	ds_read_b128 v[140:143], v140 offset:3072
	s_add_u32 s10, s10, 0x80000
	s_addc_u32 s11, s11, 0
	s_mov_b32 m0, s2
	v_lshl_add_u64 v[198:199], s[10:11], 0, v[172:173]
	ds_read_b128 v[144:147], v222 offset:32768
	ds_read_b128 v[148:151], v222 offset:33792
	ds_read_b128 v[152:155], v222 offset:34816
	ds_read_b128 v[156:159], v222 offset:35840
	ds_read_b128 v[160:163], v222 offset:36864
	ds_read_b128 v[164:167], v222 offset:37888
	ds_read_b128 v[190:193], v222 offset:38912
	ds_read_b128 v[194:197], v222 offset:39936
	global_load_lds_dwordx4 v[198:199], off
	s_mov_b32 m0, s3
	s_nop 0

	global_load_lds_dwordx4 v174, s[10:11]
	s_waitcnt lgkmcnt(8)
	s_barrier
	s_waitcnt lgkmcnt(0)


	v_mfma_f32_16x16x32_bf16 v[124:127], v[128:131], v[144:147], v[124:127]
	v_mfma_f32_16x16x32_bf16 v[116:119], v[136:139], v[144:147], v[116:119]
	v_mfma_f32_16x16x32_bf16 v[108:111], v[128:131], v[152:155], v[108:111]
	v_mfma_f32_16x16x32_bf16 v[100:103], v[136:139], v[152:155], v[100:103]
	v_mfma_f32_16x16x32_bf16 v[92:95], v[128:131], v[160:163], v[92:95]
	v_mfma_f32_16x16x32_bf16 v[84:87], v[136:139], v[160:163], v[84:87]
	v_mfma_f32_16x16x32_bf16 v[76:79], v[128:131], v[190:193], v[76:79]
	v_mfma_f32_16x16x32_bf16 v[68:71], v[136:139], v[190:193], v[68:71]
	v_mfma_f32_16x16x32_bf16 v[124:127], v[132:135], v[148:151], v[124:127]
	v_mfma_f32_16x16x32_bf16 v[116:119], v[140:143], v[148:151], v[116:119]
	v_mfma_f32_16x16x32_bf16 v[108:111], v[132:135], v[156:159], v[108:111]
	v_mfma_f32_16x16x32_bf16 v[100:103], v[140:143], v[156:159], v[100:103]
	v_mfma_f32_16x16x32_bf16 v[92:95], v[132:135], v[164:167], v[92:95]
	v_mfma_f32_16x16x32_bf16 v[84:87], v[140:143], v[164:167], v[84:87]
	v_mfma_f32_16x16x32_bf16 v[76:79], v[132:135], v[194:197], v[76:79]
	v_mfma_f32_16x16x32_bf16 v[68:71], v[140:143], v[194:197], v[68:71]

	s_barrier
	s_add_i32 s10, 0, 0x1c000
	s_add_i32 s11, s54, s57
	v_add_u32_e32 v180, s10, v179
	v_lshl_add_u64 v[230:231], v[230:231], 0, s[20:21]
	s_mov_b32 m0, s11
	ds_read_b128 v[198:201], v180
	ds_read_b128 v[202:205], v180 offset:1024
	ds_read_b128 v[206:209], v180 offset:2048
	ds_read_b128 v[226:229], v180 offset:3072
	global_load_lds_dwordx4 v[230:231], off
	s_add_i32 m0, s11, 0x2000
	v_lshl_add_u64 v[230:231], v[232:233], 0, s[20:21]

	global_load_lds_dwordx4 v[230:231], off
	s_barrier
	s_waitcnt lgkmcnt(0)


	v_mfma_f32_16x16x32_bf16 v[120:123], v[198:201], v[144:147], v[120:123]
	v_mfma_f32_16x16x32_bf16 v[112:115], v[206:209], v[144:147], v[112:115]
	v_mfma_f32_16x16x32_bf16 v[104:107], v[198:201], v[152:155], v[104:107]
	v_mfma_f32_16x16x32_bf16 v[96:99], v[206:209], v[152:155], v[96:99]
	v_mfma_f32_16x16x32_bf16 v[88:91], v[198:201], v[160:163], v[88:91]
	v_mfma_f32_16x16x32_bf16 v[80:83], v[206:209], v[160:163], v[80:83]
	v_mfma_f32_16x16x32_bf16 v[72:75], v[198:201], v[190:193], v[72:75]
	v_mfma_f32_16x16x32_bf16 v[64:67], v[206:209], v[190:193], v[64:67]
	v_mfma_f32_16x16x32_bf16 v[120:123], v[202:205], v[148:151], v[120:123]
	v_mfma_f32_16x16x32_bf16 v[112:115], v[226:229], v[148:151], v[112:115]
	v_mfma_f32_16x16x32_bf16 v[104:107], v[202:205], v[156:159], v[104:107]
	v_mfma_f32_16x16x32_bf16 v[96:99], v[226:229], v[156:159], v[96:99]
	v_mfma_f32_16x16x32_bf16 v[88:91], v[202:205], v[164:167], v[88:91]
	v_mfma_f32_16x16x32_bf16 v[80:83], v[226:229], v[164:167], v[80:83]
	v_mfma_f32_16x16x32_bf16 v[72:75], v[202:205], v[194:197], v[72:75]
	v_mfma_f32_16x16x32_bf16 v[64:67], v[226:229], v[194:197], v[64:67]

	s_mov_b32 m0, s96
	v_lshl_add_u64 v[230:231], v[234:235], 0, s[20:21]
	s_barrier
	ds_read_b128 v[144:147], v222 offset:49152
	ds_read_b128 v[148:151], v222 offset:50176
	ds_read_b128 v[152:155], v222 offset:51200
	ds_read_b128 v[156:159], v222 offset:52224
	ds_read_b128 v[160:163], v222 offset:53248
	ds_read_b128 v[164:167], v222 offset:54272
	ds_read_b128 v[190:193], v222 offset:55296
	ds_read_b128 v[194:197], v222 offset:56320
	global_load_lds_dwordx4 v[230:231], off
	s_mov_b32 m0, s97
	v_lshl_add_u64 v[230:231], v[236:237], 0, s[20:21]

	global_load_lds_dwordx4 v[230:231], off
	s_barrier
	s_waitcnt lgkmcnt(0)


	v_mfma_f32_16x16x32_bf16 v[60:63], v[128:131], v[144:147], v[60:63]
	v_mfma_f32_16x16x32_bf16 v[52:55], v[136:139], v[144:147], v[52:55]
	v_mfma_f32_16x16x32_bf16 v[44:47], v[128:131], v[152:155], v[44:47]
	v_mfma_f32_16x16x32_bf16 v[36:39], v[136:139], v[152:155], v[36:39]
	v_mfma_f32_16x16x32_bf16 v[28:31], v[128:131], v[160:163], v[28:31]
	v_mfma_f32_16x16x32_bf16 v[20:23], v[136:139], v[160:163], v[20:23]
	v_mfma_f32_16x16x32_bf16 v[12:15], v[128:131], v[190:193], v[12:15]
	v_mfma_f32_16x16x32_bf16 v[4:7], v[136:139], v[190:193], v[4:7]
	v_mfma_f32_16x16x32_bf16 v[60:63], v[132:135], v[148:151], v[60:63]
	v_mfma_f32_16x16x32_bf16 v[52:55], v[140:143], v[148:151], v[52:55]
	v_mfma_f32_16x16x32_bf16 v[44:47], v[132:135], v[156:159], v[44:47]
	v_mfma_f32_16x16x32_bf16 v[36:39], v[140:143], v[156:159], v[36:39]
	v_mfma_f32_16x16x32_bf16 v[28:31], v[132:135], v[164:167], v[28:31]
	v_mfma_f32_16x16x32_bf16 v[20:23], v[140:143], v[164:167], v[20:23]
	v_mfma_f32_16x16x32_bf16 v[12:15], v[132:135], v[194:197], v[12:15]
	v_mfma_f32_16x16x32_bf16 v[4:7], v[140:143], v[194:197], v[4:7]

	s_barrier
	s_add_u32 s8, s8, 0x80080
	s_addc_u32 s9, s9, 0
	s_add_i32 s10, s10, s57
	s_mov_b32 m0, s10
	s_nop 0

	global_load_lds_dwordx4 v172, s[8:9]
	s_add_i32 m0, s10, 0x2000
	s_nop 0

	global_load_lds_dwordx4 v174, s[8:9]
	s_waitcnt vmcnt(6)
	s_barrier

	v_mfma_f32_16x16x32_bf16 v[56:59], v[198:201], v[144:147], v[56:59]
	v_mfma_f32_16x16x32_bf16 v[48:51], v[206:209], v[144:147], v[48:51]
	v_mfma_f32_16x16x32_bf16 v[40:43], v[198:201], v[152:155], v[40:43]
	v_mfma_f32_16x16x32_bf16 v[32:35], v[206:209], v[152:155], v[32:35]
	v_mfma_f32_16x16x32_bf16 v[24:27], v[198:201], v[160:163], v[24:27]
	v_mfma_f32_16x16x32_bf16 v[16:19], v[206:209], v[160:163], v[16:19]
	v_mfma_f32_16x16x32_bf16 v[8:11], v[198:201], v[190:193], v[8:11]
	v_mfma_f32_16x16x32_bf16 v[0:3], v[206:209], v[190:193], v[0:3]
	v_mfma_f32_16x16x32_bf16 v[56:59], v[202:205], v[148:151], v[56:59]
	v_mfma_f32_16x16x32_bf16 v[48:51], v[226:229], v[148:151], v[48:51]
	v_mfma_f32_16x16x32_bf16 v[40:43], v[202:205], v[156:159], v[40:43]
	v_mfma_f32_16x16x32_bf16 v[32:35], v[226:229], v[156:159], v[32:35]
	v_mfma_f32_16x16x32_bf16 v[24:27], v[202:205], v[164:167], v[24:27]
	v_mfma_f32_16x16x32_bf16 v[16:19], v[226:229], v[164:167], v[16:19]
	v_mfma_f32_16x16x32_bf16 v[8:11], v[202:205], v[194:197], v[8:11]
	v_mfma_f32_16x16x32_bf16 v[0:3], v[226:229], v[194:197], v[0:3]

	s_add_i32 s53, s53, 2
	s_add_u32 s6, s6, 0x100
	s_addc_u32 s7, s7, 0
	s_add_u32 s51, s51, 0x100
	s_addc_u32 s52, s52, 0
	s_cmp_gt_u32 s53, 29
	s_barrier
	s_cbranch_scc0 .LBB0_118
	v_mov_b32_e32 v142, v210
	v_mov_b32_e32 v143, v169
	s_lshl_b32 s33, s4, 8
	s_add_i32 s33, s33, s34
	v_lshl_add_u32 v133, v142, 4, v143
	v_ashrrev_i32_e32 v198, 2, v133
	v_and_b32_e32 v192, 3, v143
	v_and_b32_e32 v128, -4, v133
	s_cmp_gt_i32 s4, 30
	v_lshl_add_u32 v226, v192, 6, v128
	v_add_u32_e32 v190, s33, v198
	s_cselect_b64 s[52:53], -1, 0
	s_cmp_gt_i32 s50, 8
	s_mov_b64 s[4:5], -1
	s_cbranch_scc0 .LBB0_419
	s_cmp_lg_u32 s50, 9
	s_cbranch_scc0 .LBB0_225
	s_cmp_gt_u32 s50, 25
	s_cbranch_scc0 .LBB0_127
	v_mul_f32_e32 v130, 0xbfb8aa3b, v120
	v_mul_f32_e32 v131, 0xbfb8aa3b, v121
	v_mul_f32_e32 v132, 0xbfb8aa3b, v122
	v_mul_f32_e32 v134, 0xbfb8aa3b, v123
	v_mul_f32_e32 v135, 0xbfb8aa3b, v112
	v_mul_f32_e32 v136, 0xbfb8aa3b, v113
	v_mul_f32_e32 v137, 0xbfb8aa3b, v114
	v_mul_f32_e32 v138, 0xbfb8aa3b, v115
	v_mul_f32_e32 v139, 0xbfb8aa3b, v104
	v_mul_f32_e32 v140, 0xbfb8aa3b, v105
	v_mul_f32_e32 v141, 0xbfb8aa3b, v106
	v_mul_f32_e32 v144, 0xbfb8aa3b, v107
	v_mul_f32_e32 v145, 0xbfb8aa3b, v96
	v_mul_f32_e32 v146, 0xbfb8aa3b, v97
	v_mul_f32_e32 v147, 0xbfb8aa3b, v98
	v_mul_f32_e32 v148, 0xbfb8aa3b, v99
	v_mul_f32_e32 v149, 0xbfb8aa3b, v88
	v_mul_f32_e32 v150, 0xbfb8aa3b, v89
	v_mul_f32_e32 v151, 0xbfb8aa3b, v90
	v_mul_f32_e32 v152, 0xbfb8aa3b, v91
	v_mul_f32_e32 v153, 0xbfb8aa3b, v80
	v_mul_f32_e32 v154, 0xbfb8aa3b, v81
	v_mul_f32_e32 v155, 0xbfb8aa3b, v82
	v_mul_f32_e32 v180, 0xbfb8aa3b, v83
	v_mul_f32_e32 v206, 0xbfb8aa3b, v72
	v_mul_f32_e32 v207, 0xbfb8aa3b, v73
	v_mul_f32_e32 v208, 0xbfb8aa3b, v74
	v_mul_f32_e32 v209, 0xbfb8aa3b, v75
	v_mul_f32_e32 v227, 0xbfb8aa3b, v64
	v_mul_f32_e32 v228, 0xbfb8aa3b, v65
	v_mul_f32_e32 v229, 0xbfb8aa3b, v66
	v_mul_f32_e32 v230, 0xbfb8aa3b, v67
	v_exp_f32_e32 v205, v130
	v_exp_f32_e32 v204, v131
	v_exp_f32_e32 v203, v132
	v_exp_f32_e32 v202, v134
	v_exp_f32_e32 v200, v135
	v_exp_f32_e32 v199, v136
	v_exp_f32_e32 v197, v137
	v_exp_f32_e32 v196, v138
	v_exp_f32_e32 v195, v139
	v_exp_f32_e32 v194, v140
	v_exp_f32_e32 v193, v141
	v_exp_f32_e32 v167, v144
	v_exp_f32_e32 v166, v145
	v_exp_f32_e32 v165, v146
	v_exp_f32_e32 v164, v147
	v_exp_f32_e32 v163, v148
	v_exp_f32_e32 v162, v149
	v_exp_f32_e32 v161, v150
	v_exp_f32_e32 v160, v151
	v_exp_f32_e32 v159, v152
	v_exp_f32_e32 v158, v153
	v_exp_f32_e32 v157, v154
	v_exp_f32_e32 v156, v155
	v_exp_f32_e32 v155, v180
	v_exp_f32_e32 v154, v206
	v_exp_f32_e32 v153, v207
	v_exp_f32_e32 v152, v208
	v_exp_f32_e32 v151, v209
	v_exp_f32_e32 v150, v227
	v_exp_f32_e32 v149, v228
	v_exp_f32_e32 v148, v229
	v_exp_f32_e32 v147, v230
	v_ashrrev_i32_e32 v191, 31, v190
	s_cmp_lt_u32 s50, 42
	v_lshlrev_b32_e32 v201, 2, v192
	v_lshlrev_b64 v[128:129], 12, v[190:191]
	v_mul_f32_e32 v146, 0xbfb8aa3b, v56
	v_mul_f32_e32 v145, 0xbfb8aa3b, v57
	v_mul_f32_e32 v144, 0xbfb8aa3b, v58
	v_mul_f32_e32 v141, 0xbfb8aa3b, v59
	v_mul_f32_e32 v140, 0xbfb8aa3b, v48
	v_mul_f32_e32 v139, 0xbfb8aa3b, v49
	v_mul_f32_e32 v138, 0xbfb8aa3b, v50
	v_mul_f32_e32 v137, 0xbfb8aa3b, v51
	v_mul_f32_e32 v136, 0xbfb8aa3b, v40
	v_mul_f32_e32 v135, 0xbfb8aa3b, v41
	v_mul_f32_e32 v134, 0xbfb8aa3b, v42
	v_mul_f32_e32 v132, 0xbfb8aa3b, v43
	s_cbranch_scc1 .LBB0_124
	v_mul_f32_e32 v130, 0xbfb8aa3b, v124
	v_mul_f32_e32 v131, 0xbfb8aa3b, v125
	v_mul_f32_e32 v206, 0xbfb8aa3b, v126
	v_mul_f32_e32 v207, 0xbfb8aa3b, v127
	v_exp_f32_e32 v130, v130
	v_exp_f32_e32 v131, v131
	v_exp_f32_e32 v206, v206
	v_exp_f32_e32 v207, v207
	v_add_f32_e32 v130, 1.0, v130
	v_add_f32_e32 v131, 1.0, v131
	v_add_f32_e32 v206, 1.0, v206
	v_add_f32_e32 v207, 1.0, v207
	v_rcp_f32_e32 v130, v130
	v_rcp_f32_e32 v131, v131
	v_rcp_f32_e32 v206, v206
	v_rcp_f32_e32 v207, v207
	s_lshl_b32 s4, s50, 8
	v_cvt_pk_bf16_f32 v130, v130, v131
	s_add_i32 s4, s28, s4
	v_cvt_pk_bf16_f32 v131, v206, v207
	ds_bpermute_b32 v206, v226, v130
	ds_bpermute_b32 v207, v226, v131
	v_or_b32_e32 v180, s4, v201
	v_lshl_add_u64 v[130:131], s[40:41], 0, v[128:129]
	v_lshlrev_b64 v[208:209], 1, v[180:181]
	v_lshl_add_u64 v[130:131], v[130:131], 0, v[208:209]
	s_waitcnt lgkmcnt(0)
	global_store_dwordx2 v[130:131], v[206:207], off
	v_mul_f32_e32 v180, 0xbfb8aa3b, v116
	v_mul_f32_e32 v206, 0xbfb8aa3b, v117
	v_mul_f32_e32 v207, 0xbfb8aa3b, v118
	v_mul_f32_e32 v208, 0xbfb8aa3b, v119
	v_exp_f32_e32 v180, v180
	v_exp_f32_e32 v206, v206
	v_exp_f32_e32 v207, v207
	v_exp_f32_e32 v208, v208
	v_add_f32_e32 v180, 1.0, v180
	v_add_f32_e32 v206, 1.0, v206
	v_add_f32_e32 v207, 1.0, v207
	v_add_f32_e32 v208, 1.0, v208
	v_rcp_f32_e32 v180, v180
	v_rcp_f32_e32 v206, v206
	v_rcp_f32_e32 v207, v207
	v_rcp_f32_e32 v208, v208
	s_mov_b64 s[4:5], 0x10000
	v_cvt_pk_bf16_f32 v180, v180, v206
	ds_bpermute_b32 v206, v226, v180
	v_cvt_pk_bf16_f32 v207, v207, v208
	ds_bpermute_b32 v207, v226, v207
	v_add_f32_e32 v180, 1.0, v205
	v_add_f32_e32 v208, 1.0, v202
	v_rcp_f32_e32 v180, v180
	v_rcp_f32_e32 v208, v208
	s_waitcnt lgkmcnt(0)
	global_store_dwordx2 v[130:131], v[206:207], off offset:32
	v_add_f32_e32 v206, 1.0, v204
	v_add_f32_e32 v207, 1.0, v203
	v_rcp_f32_e32 v206, v206
	v_rcp_f32_e32 v207, v207
	v_mul_f32_e32 v227, 0xbfb8aa3b, v103
	v_exp_f32_e32 v227, v227
	v_cvt_pk_bf16_f32 v180, v180, v206
	v_cvt_pk_bf16_f32 v207, v207, v208
	ds_bpermute_b32 v206, v226, v180
	ds_bpermute_b32 v207, v226, v207
	v_add_f32_e32 v180, 1.0, v200
	v_add_f32_e32 v208, 1.0, v196
	v_rcp_f32_e32 v180, v180
	v_rcp_f32_e32 v208, v208
	s_waitcnt lgkmcnt(0)
	global_store_dwordx2 v[130:131], v[206:207], off offset:256
	v_add_f32_e32 v206, 1.0, v199
	v_add_f32_e32 v207, 1.0, v197
	v_rcp_f32_e32 v206, v206
	v_rcp_f32_e32 v207, v207
	v_add_f32_e32 v227, 1.0, v227
	v_rcp_f32_e32 v227, v227
	v_cvt_pk_bf16_f32 v180, v180, v206
	v_cvt_pk_bf16_f32 v207, v207, v208
	ds_bpermute_b32 v206, v226, v180
	ds_bpermute_b32 v207, v226, v207
	v_mul_f32_e32 v180, 0xbfb8aa3b, v108
	v_mul_f32_e32 v208, 0xbfb8aa3b, v111
	v_exp_f32_e32 v180, v180
	v_exp_f32_e32 v208, v208
	s_waitcnt lgkmcnt(0)
	global_store_dwordx2 v[130:131], v[206:207], off offset:288
	v_mul_f32_e32 v206, 0xbfb8aa3b, v109
	v_mul_f32_e32 v207, 0xbfb8aa3b, v110
	v_exp_f32_e32 v206, v206
	v_exp_f32_e32 v207, v207
	v_add_f32_e32 v180, 1.0, v180
	v_add_f32_e32 v208, 1.0, v208
	v_add_f32_e32 v206, 1.0, v206
	v_add_f32_e32 v207, 1.0, v207
	v_rcp_f32_e32 v180, v180
	v_rcp_f32_e32 v206, v206
	v_rcp_f32_e32 v207, v207
	v_rcp_f32_e32 v208, v208
	v_cvt_pk_bf16_f32 v180, v180, v206
	ds_bpermute_b32 v206, v226, v180
	v_cvt_pk_bf16_f32 v207, v207, v208
	ds_bpermute_b32 v207, v226, v207
	v_lshl_add_u64 v[208:209], v[130:131], 0, s[4:5]
	s_mov_b32 s4, 0x10000
	v_add_co_u32_e32 v228, vcc, s4, v130
	v_mul_f32_e32 v180, 0xbfb8aa3b, v100
	s_nop 0
	v_addc_co_u32_e32 v229, vcc, 0, v131, vcc
	s_waitcnt lgkmcnt(0)
	global_store_dwordx2 v[228:229], v[206:207], off
	v_mul_f32_e32 v206, 0xbfb8aa3b, v101
	v_mul_f32_e32 v207, 0xbfb8aa3b, v102
	v_exp_f32_e32 v180, v180
	v_exp_f32_e32 v206, v206
	v_exp_f32_e32 v207, v207
	s_mov_b64 s[4:5], 0x20000
	v_add_f32_e32 v180, 1.0, v180
	v_add_f32_e32 v206, 1.0, v206
	v_add_f32_e32 v207, 1.0, v207
	v_rcp_f32_e32 v180, v180
	v_rcp_f32_e32 v206, v206
	v_rcp_f32_e32 v207, v207
	v_cvt_pk_bf16_f32 v180, v180, v206
	v_cvt_pk_bf16_f32 v207, v207, v227
	ds_bpermute_b32 v206, v226, v180
	ds_bpermute_b32 v207, v226, v207
	v_add_f32_e32 v180, 1.0, v195
	v_add_f32_e32 v227, 1.0, v167
	v_rcp_f32_e32 v180, v180
	v_rcp_f32_e32 v227, v227
	s_waitcnt lgkmcnt(0)
	global_store_dwordx2 v[208:209], v[206:207], off offset:32
	v_add_f32_e32 v206, 1.0, v194
	v_add_f32_e32 v207, 1.0, v193
	v_rcp_f32_e32 v206, v206
	v_rcp_f32_e32 v207, v207
	v_cvt_pk_bf16_f32 v180, v180, v206
	v_cvt_pk_bf16_f32 v207, v207, v227
	ds_bpermute_b32 v206, v226, v180
	ds_bpermute_b32 v207, v226, v207
	v_add_f32_e32 v180, 1.0, v166
	v_add_f32_e32 v227, 1.0, v163
	v_rcp_f32_e32 v180, v180
	v_rcp_f32_e32 v227, v227
	s_waitcnt lgkmcnt(0)
	global_store_dwordx2 v[208:209], v[206:207], off offset:256
	v_add_f32_e32 v206, 1.0, v165
	v_add_f32_e32 v207, 1.0, v164
	v_rcp_f32_e32 v206, v206
	v_rcp_f32_e32 v207, v207
	v_cvt_pk_bf16_f32 v180, v180, v206
	v_cvt_pk_bf16_f32 v207, v207, v227
	ds_bpermute_b32 v206, v226, v180
	ds_bpermute_b32 v207, v226, v207
	v_mul_f32_e32 v180, 0xbfb8aa3b, v92
	v_exp_f32_e32 v180, v180
	v_mul_f32_e32 v227, 0xbfb8aa3b, v87
	v_exp_f32_e32 v227, v227
	s_waitcnt lgkmcnt(0)
	global_store_dwordx2 v[208:209], v[206:207], off offset:288
	v_mul_f32_e32 v206, 0xbfb8aa3b, v93
	v_mul_f32_e32 v207, 0xbfb8aa3b, v94
	v_mul_f32_e32 v208, 0xbfb8aa3b, v95
	v_exp_f32_e32 v206, v206
	v_exp_f32_e32 v207, v207
	v_exp_f32_e32 v208, v208
	v_add_f32_e32 v180, 1.0, v180
	v_add_f32_e32 v206, 1.0, v206
	v_add_f32_e32 v207, 1.0, v207
	v_add_f32_e32 v208, 1.0, v208
	v_rcp_f32_e32 v180, v180
	v_rcp_f32_e32 v206, v206
	v_rcp_f32_e32 v207, v207
	v_rcp_f32_e32 v208, v208
	v_add_f32_e32 v227, 1.0, v227
	v_cvt_pk_bf16_f32 v180, v180, v206
	ds_bpermute_b32 v206, v226, v180
	v_cvt_pk_bf16_f32 v207, v207, v208
	ds_bpermute_b32 v207, v226, v207
	v_lshl_add_u64 v[208:209], v[130:131], 0, s[4:5]
	s_mov_b32 s4, 0x20000
	v_add_co_u32_e32 v228, vcc, s4, v130
	v_mul_f32_e32 v180, 0xbfb8aa3b, v84
	s_nop 0
	v_addc_co_u32_e32 v229, vcc, 0, v131, vcc
	s_waitcnt lgkmcnt(0)
	global_store_dwordx2 v[228:229], v[206:207], off
	v_mul_f32_e32 v206, 0xbfb8aa3b, v85
	v_mul_f32_e32 v207, 0xbfb8aa3b, v86
	v_exp_f32_e32 v180, v180
	v_exp_f32_e32 v206, v206
	v_exp_f32_e32 v207, v207
	v_rcp_f32_e32 v227, v227
	v_add_f32_e32 v180, 1.0, v180
	v_add_f32_e32 v206, 1.0, v206
	v_add_f32_e32 v207, 1.0, v207
	v_rcp_f32_e32 v180, v180
	v_rcp_f32_e32 v206, v206
	v_rcp_f32_e32 v207, v207
	s_mov_b64 s[4:5], 0x30000
	v_cvt_pk_bf16_f32 v180, v180, v206
	v_cvt_pk_bf16_f32 v207, v207, v227
	ds_bpermute_b32 v206, v226, v180
	ds_bpermute_b32 v207, v226, v207
	v_add_f32_e32 v180, 1.0, v162
	v_add_f32_e32 v227, 1.0, v159
	v_rcp_f32_e32 v180, v180
	v_rcp_f32_e32 v227, v227
	s_waitcnt lgkmcnt(0)
	global_store_dwordx2 v[208:209], v[206:207], off offset:32
	v_add_f32_e32 v206, 1.0, v161
	v_add_f32_e32 v207, 1.0, v160
	v_rcp_f32_e32 v206, v206
	v_rcp_f32_e32 v207, v207
	v_cvt_pk_bf16_f32 v180, v180, v206
	v_cvt_pk_bf16_f32 v207, v207, v227
	ds_bpermute_b32 v206, v226, v180
	ds_bpermute_b32 v207, v226, v207
	v_add_f32_e32 v180, 1.0, v158
	v_add_f32_e32 v227, 1.0, v155
	v_rcp_f32_e32 v180, v180
	v_rcp_f32_e32 v227, v227
	s_waitcnt lgkmcnt(0)
	global_store_dwordx2 v[208:209], v[206:207], off offset:256
	v_add_f32_e32 v206, 1.0, v157
	v_add_f32_e32 v207, 1.0, v156
	v_rcp_f32_e32 v206, v206
	v_rcp_f32_e32 v207, v207
	v_cvt_pk_bf16_f32 v180, v180, v206
	v_cvt_pk_bf16_f32 v207, v207, v227
	ds_bpermute_b32 v206, v226, v180
	ds_bpermute_b32 v207, v226, v207
	v_mul_f32_e32 v180, 0xbfb8aa3b, v76
	v_exp_f32_e32 v180, v180
	v_mul_f32_e32 v227, 0xbfb8aa3b, v71
	v_exp_f32_e32 v227, v227
	s_waitcnt lgkmcnt(0)
	global_store_dwordx2 v[208:209], v[206:207], off offset:288
	v_mul_f32_e32 v206, 0xbfb8aa3b, v77
	v_mul_f32_e32 v207, 0xbfb8aa3b, v78
	v_mul_f32_e32 v208, 0xbfb8aa3b, v79
	v_exp_f32_e32 v206, v206
	v_exp_f32_e32 v207, v207
	v_exp_f32_e32 v208, v208
	v_add_f32_e32 v180, 1.0, v180
	v_add_f32_e32 v206, 1.0, v206
	v_add_f32_e32 v207, 1.0, v207
	v_add_f32_e32 v208, 1.0, v208
	v_rcp_f32_e32 v180, v180
	v_rcp_f32_e32 v206, v206
	v_rcp_f32_e32 v207, v207
	v_rcp_f32_e32 v208, v208
	v_add_f32_e32 v227, 1.0, v227
	v_cvt_pk_bf16_f32 v180, v180, v206
	ds_bpermute_b32 v206, v226, v180
	v_cvt_pk_bf16_f32 v207, v207, v208
	ds_bpermute_b32 v207, v226, v207
	v_lshl_add_u64 v[208:209], v[130:131], 0, s[4:5]
	s_mov_b32 s4, 0x30000
	v_add_co_u32_e32 v228, vcc, s4, v130
	v_mul_f32_e32 v180, 0xbfb8aa3b, v68
	s_nop 0
	v_addc_co_u32_e32 v229, vcc, 0, v131, vcc
	s_waitcnt lgkmcnt(0)
	global_store_dwordx2 v[228:229], v[206:207], off
	v_mul_f32_e32 v206, 0xbfb8aa3b, v69
	v_mul_f32_e32 v207, 0xbfb8aa3b, v70
	v_exp_f32_e32 v180, v180
	v_exp_f32_e32 v206, v206
	v_exp_f32_e32 v207, v207
	v_rcp_f32_e32 v227, v227
	v_add_f32_e32 v180, 1.0, v180
	v_add_f32_e32 v206, 1.0, v206
	v_add_f32_e32 v207, 1.0, v207
	v_rcp_f32_e32 v180, v180
	v_rcp_f32_e32 v206, v206
	v_rcp_f32_e32 v207, v207
	s_mov_b64 s[4:5], 0x80000
	v_cvt_pk_bf16_f32 v180, v180, v206
	v_cvt_pk_bf16_f32 v207, v207, v227
	ds_bpermute_b32 v206, v226, v180
	ds_bpermute_b32 v207, v226, v207
	v_add_f32_e32 v180, 1.0, v154
	v_add_f32_e32 v227, 1.0, v151
	v_rcp_f32_e32 v180, v180
	v_rcp_f32_e32 v227, v227
	s_waitcnt lgkmcnt(0)
	global_store_dwordx2 v[208:209], v[206:207], off offset:32
	v_add_f32_e32 v206, 1.0, v153
	v_add_f32_e32 v207, 1.0, v152
	v_rcp_f32_e32 v206, v206
	v_rcp_f32_e32 v207, v207
	v_cvt_pk_bf16_f32 v180, v180, v206
	v_cvt_pk_bf16_f32 v207, v207, v227
	ds_bpermute_b32 v206, v226, v180
	ds_bpermute_b32 v207, v226, v207
	v_add_f32_e32 v180, 1.0, v150
	v_add_f32_e32 v227, 1.0, v147
	v_rcp_f32_e32 v180, v180
	v_rcp_f32_e32 v227, v227
	s_waitcnt lgkmcnt(0)
	global_store_dwordx2 v[208:209], v[206:207], off offset:256
	v_add_f32_e32 v206, 1.0, v149
	v_add_f32_e32 v207, 1.0, v148
	v_rcp_f32_e32 v206, v206
	v_rcp_f32_e32 v207, v207
	v_cvt_pk_bf16_f32 v180, v180, v206
	v_cvt_pk_bf16_f32 v207, v207, v227
	ds_bpermute_b32 v206, v226, v180
	ds_bpermute_b32 v207, v226, v207
	v_mul_f32_e32 v180, 0xbfb8aa3b, v60
	v_exp_f32_e32 v180, v180
	v_mul_f32_e32 v227, 0xbfb8aa3b, v55
	v_exp_f32_e32 v227, v227
	s_waitcnt lgkmcnt(0)
	global_store_dwordx2 v[208:209], v[206:207], off offset:288
	v_mul_f32_e32 v206, 0xbfb8aa3b, v61
	v_mul_f32_e32 v207, 0xbfb8aa3b, v62
	v_mul_f32_e32 v208, 0xbfb8aa3b, v63
	v_exp_f32_e32 v206, v206
	v_exp_f32_e32 v207, v207
	v_exp_f32_e32 v208, v208
	v_add_f32_e32 v180, 1.0, v180
	v_add_f32_e32 v206, 1.0, v206
	v_add_f32_e32 v207, 1.0, v207
	v_add_f32_e32 v208, 1.0, v208
	v_rcp_f32_e32 v180, v180
	v_rcp_f32_e32 v206, v206
	v_rcp_f32_e32 v207, v207
	v_rcp_f32_e32 v208, v208
	v_add_f32_e32 v227, 1.0, v227
	v_cvt_pk_bf16_f32 v180, v180, v206
	ds_bpermute_b32 v206, v226, v180
	v_cvt_pk_bf16_f32 v207, v207, v208
	ds_bpermute_b32 v207, v226, v207
	v_lshl_add_u64 v[208:209], v[130:131], 0, s[4:5]
	s_mov_b32 s4, 0x80000
	v_add_co_u32_e32 v228, vcc, s4, v130
	v_mul_f32_e32 v180, 0xbfb8aa3b, v52
	s_nop 0
	v_addc_co_u32_e32 v229, vcc, 0, v131, vcc
	s_waitcnt lgkmcnt(0)
	global_store_dwordx2 v[228:229], v[206:207], off
	v_mul_f32_e32 v206, 0xbfb8aa3b, v53
	v_mul_f32_e32 v207, 0xbfb8aa3b, v54
	v_exp_f32_e32 v180, v180
	v_exp_f32_e32 v206, v206
	v_exp_f32_e32 v207, v207
	v_rcp_f32_e32 v227, v227
	v_add_f32_e32 v180, 1.0, v180
	v_add_f32_e32 v206, 1.0, v206
	v_add_f32_e32 v207, 1.0, v207
	v_rcp_f32_e32 v180, v180
	v_rcp_f32_e32 v206, v206
	v_rcp_f32_e32 v207, v207
	s_mov_b64 s[4:5], 0x90000
	v_cvt_pk_bf16_f32 v180, v180, v206
	v_cvt_pk_bf16_f32 v207, v207, v227
	ds_bpermute_b32 v206, v226, v180
	ds_bpermute_b32 v207, v226, v207
	v_exp_f32_e32 v180, v146
	v_exp_f32_e32 v227, v141
	s_waitcnt lgkmcnt(0)
	global_store_dwordx2 v[208:209], v[206:207], off offset:32
	v_exp_f32_e32 v206, v145
	v_exp_f32_e32 v207, v144
	v_add_f32_e32 v180, 1.0, v180
	v_add_f32_e32 v227, 1.0, v227
	v_add_f32_e32 v206, 1.0, v206
	v_add_f32_e32 v207, 1.0, v207
	v_rcp_f32_e32 v180, v180
	v_rcp_f32_e32 v206, v206
	v_rcp_f32_e32 v207, v207
	v_rcp_f32_e32 v227, v227
	v_cvt_pk_bf16_f32 v180, v180, v206
	ds_bpermute_b32 v206, v226, v180
	v_cvt_pk_bf16_f32 v207, v207, v227
	ds_bpermute_b32 v207, v226, v207
	v_exp_f32_e32 v180, v140
	v_exp_f32_e32 v227, v137
	s_waitcnt lgkmcnt(0)
	global_store_dwordx2 v[208:209], v[206:207], off offset:256
	v_exp_f32_e32 v206, v139
	v_exp_f32_e32 v207, v138
	v_add_f32_e32 v180, 1.0, v180
	v_add_f32_e32 v227, 1.0, v227
	v_add_f32_e32 v206, 1.0, v206
	v_add_f32_e32 v207, 1.0, v207
	v_rcp_f32_e32 v180, v180
	v_rcp_f32_e32 v206, v206
	v_rcp_f32_e32 v207, v207
	v_rcp_f32_e32 v227, v227
	v_cvt_pk_bf16_f32 v180, v180, v206
	ds_bpermute_b32 v206, v226, v180
	v_cvt_pk_bf16_f32 v207, v207, v227
	ds_bpermute_b32 v207, v226, v207
	v_mul_f32_e32 v180, 0xbfb8aa3b, v44
	v_exp_f32_e32 v180, v180
	v_mul_f32_e32 v227, 0xbfb8aa3b, v39
	v_exp_f32_e32 v227, v227
	s_waitcnt lgkmcnt(0)
	global_store_dwordx2 v[208:209], v[206:207], off offset:288
	v_mul_f32_e32 v206, 0xbfb8aa3b, v45
	v_mul_f32_e32 v207, 0xbfb8aa3b, v46
	v_mul_f32_e32 v208, 0xbfb8aa3b, v47
	v_exp_f32_e32 v206, v206
	v_exp_f32_e32 v207, v207
	v_exp_f32_e32 v208, v208
	v_add_f32_e32 v180, 1.0, v180
	v_add_f32_e32 v206, 1.0, v206
	v_add_f32_e32 v207, 1.0, v207
	v_add_f32_e32 v208, 1.0, v208
	v_rcp_f32_e32 v180, v180
	v_rcp_f32_e32 v206, v206
	v_rcp_f32_e32 v207, v207
	v_rcp_f32_e32 v208, v208
	v_add_f32_e32 v227, 1.0, v227
	v_cvt_pk_bf16_f32 v180, v180, v206
	ds_bpermute_b32 v206, v226, v180
	v_cvt_pk_bf16_f32 v207, v207, v208
	ds_bpermute_b32 v207, v226, v207
	v_lshl_add_u64 v[208:209], v[130:131], 0, s[4:5]
	s_mov_b32 s4, 0x90000
	v_add_co_u32_e32 v228, vcc, s4, v130
	v_mul_f32_e32 v180, 0xbfb8aa3b, v36
	s_nop 0
	v_addc_co_u32_e32 v229, vcc, 0, v131, vcc
	s_waitcnt lgkmcnt(0)
	global_store_dwordx2 v[228:229], v[206:207], off
	v_mul_f32_e32 v206, 0xbfb8aa3b, v37
	v_mul_f32_e32 v207, 0xbfb8aa3b, v38
	v_exp_f32_e32 v180, v180
	v_exp_f32_e32 v206, v206
	v_exp_f32_e32 v207, v207
	v_rcp_f32_e32 v227, v227
	v_add_f32_e32 v180, 1.0, v180
	v_add_f32_e32 v206, 1.0, v206
	v_add_f32_e32 v207, 1.0, v207
	v_rcp_f32_e32 v180, v180
	v_rcp_f32_e32 v206, v206
	v_rcp_f32_e32 v207, v207
	s_mov_b64 s[4:5], 0xa0000
	v_cvt_pk_bf16_f32 v180, v180, v206
	v_cvt_pk_bf16_f32 v207, v207, v227
	ds_bpermute_b32 v206, v226, v180
	ds_bpermute_b32 v207, v226, v207
	v_exp_f32_e32 v180, v136
	v_exp_f32_e32 v227, v132
	s_waitcnt lgkmcnt(0)
	global_store_dwordx2 v[208:209], v[206:207], off offset:32
	v_exp_f32_e32 v206, v135
	v_exp_f32_e32 v207, v134
	v_add_f32_e32 v180, 1.0, v180
	v_add_f32_e32 v227, 1.0, v227
	v_add_f32_e32 v206, 1.0, v206
	v_add_f32_e32 v207, 1.0, v207
	v_rcp_f32_e32 v180, v180
	v_rcp_f32_e32 v206, v206
	v_rcp_f32_e32 v207, v207
	v_rcp_f32_e32 v227, v227
	v_cvt_pk_bf16_f32 v180, v180, v206
	ds_bpermute_b32 v206, v226, v180
	v_cvt_pk_bf16_f32 v207, v207, v227
	ds_bpermute_b32 v207, v226, v207
	v_mul_f32_e32 v180, 0xbfb8aa3b, v32
	v_mul_f32_e32 v227, 0xbfb8aa3b, v35
	v_exp_f32_e32 v180, v180
	v_exp_f32_e32 v227, v227
	s_waitcnt lgkmcnt(0)
	global_store_dwordx2 v[208:209], v[206:207], off offset:256
	v_mul_f32_e32 v206, 0xbfb8aa3b, v33
	v_mul_f32_e32 v207, 0xbfb8aa3b, v34
	v_exp_f32_e32 v206, v206
	v_exp_f32_e32 v207, v207
	v_add_f32_e32 v180, 1.0, v180
	v_add_f32_e32 v227, 1.0, v227
	v_add_f32_e32 v206, 1.0, v206
	v_add_f32_e32 v207, 1.0, v207
	v_rcp_f32_e32 v180, v180
	v_rcp_f32_e32 v206, v206
	v_rcp_f32_e32 v207, v207
	v_rcp_f32_e32 v227, v227
	v_cvt_pk_bf16_f32 v180, v180, v206
	ds_bpermute_b32 v206, v226, v180
	v_cvt_pk_bf16_f32 v207, v207, v227
	ds_bpermute_b32 v207, v226, v207
	v_mul_f32_e32 v180, 0xbfb8aa3b, v28
	v_exp_f32_e32 v180, v180
	v_mul_f32_e32 v227, 0xbfb8aa3b, v23
	v_exp_f32_e32 v227, v227
	s_waitcnt lgkmcnt(0)
	global_store_dwordx2 v[208:209], v[206:207], off offset:288
	v_mul_f32_e32 v206, 0xbfb8aa3b, v29
	v_mul_f32_e32 v207, 0xbfb8aa3b, v30
	v_mul_f32_e32 v208, 0xbfb8aa3b, v31
	v_exp_f32_e32 v206, v206
	v_exp_f32_e32 v207, v207
	v_exp_f32_e32 v208, v208
	v_add_f32_e32 v180, 1.0, v180
	v_add_f32_e32 v206, 1.0, v206
	v_add_f32_e32 v207, 1.0, v207
	v_add_f32_e32 v208, 1.0, v208
	v_rcp_f32_e32 v180, v180
	v_rcp_f32_e32 v206, v206
	v_rcp_f32_e32 v207, v207
	v_rcp_f32_e32 v208, v208
	v_add_f32_e32 v227, 1.0, v227
	v_cvt_pk_bf16_f32 v180, v180, v206
	ds_bpermute_b32 v206, v226, v180
	v_cvt_pk_bf16_f32 v207, v207, v208
	ds_bpermute_b32 v207, v226, v207
	v_lshl_add_u64 v[208:209], v[130:131], 0, s[4:5]
	s_mov_b32 s4, 0xa0000
	v_add_co_u32_e32 v228, vcc, s4, v130
	v_mul_f32_e32 v180, 0xbfb8aa3b, v20
	s_nop 0
	v_addc_co_u32_e32 v229, vcc, 0, v131, vcc
	s_waitcnt lgkmcnt(0)
	global_store_dwordx2 v[228:229], v[206:207], off
	v_mul_f32_e32 v206, 0xbfb8aa3b, v21
	v_mul_f32_e32 v207, 0xbfb8aa3b, v22
	v_exp_f32_e32 v180, v180
	v_exp_f32_e32 v206, v206
	v_exp_f32_e32 v207, v207
	v_rcp_f32_e32 v227, v227
	v_add_f32_e32 v180, 1.0, v180
	v_add_f32_e32 v206, 1.0, v206
	v_add_f32_e32 v207, 1.0, v207
	v_rcp_f32_e32 v180, v180
	v_rcp_f32_e32 v206, v206
	v_rcp_f32_e32 v207, v207
	s_mov_b64 s[4:5], 0xb0000
	v_cvt_pk_bf16_f32 v180, v180, v206
	v_cvt_pk_bf16_f32 v207, v207, v227
	ds_bpermute_b32 v206, v226, v180
	ds_bpermute_b32 v207, v226, v207
	v_mul_f32_e32 v180, 0xbfb8aa3b, v24
	v_mul_f32_e32 v227, 0xbfb8aa3b, v27
	v_exp_f32_e32 v180, v180
	v_exp_f32_e32 v227, v227
	s_waitcnt lgkmcnt(0)
	global_store_dwordx2 v[208:209], v[206:207], off offset:32
	v_mul_f32_e32 v206, 0xbfb8aa3b, v25
	v_mul_f32_e32 v207, 0xbfb8aa3b, v26
	v_exp_f32_e32 v206, v206
	v_exp_f32_e32 v207, v207
	v_add_f32_e32 v180, 1.0, v180
	v_add_f32_e32 v227, 1.0, v227
	v_add_f32_e32 v206, 1.0, v206
	v_add_f32_e32 v207, 1.0, v207
	v_rcp_f32_e32 v180, v180
	v_rcp_f32_e32 v206, v206
	v_rcp_f32_e32 v207, v207
	v_rcp_f32_e32 v227, v227
	v_cvt_pk_bf16_f32 v180, v180, v206
	ds_bpermute_b32 v206, v226, v180
	v_cvt_pk_bf16_f32 v207, v207, v227
	ds_bpermute_b32 v207, v226, v207
	v_mul_f32_e32 v180, 0xbfb8aa3b, v16
	v_mul_f32_e32 v227, 0xbfb8aa3b, v19
	v_exp_f32_e32 v180, v180
	v_exp_f32_e32 v227, v227
	s_waitcnt lgkmcnt(0)
	global_store_dwordx2 v[208:209], v[206:207], off offset:256
	v_mul_f32_e32 v206, 0xbfb8aa3b, v17
	v_mul_f32_e32 v207, 0xbfb8aa3b, v18
	v_exp_f32_e32 v206, v206
	v_exp_f32_e32 v207, v207
	v_add_f32_e32 v180, 1.0, v180
	v_add_f32_e32 v227, 1.0, v227
	v_add_f32_e32 v206, 1.0, v206
	v_add_f32_e32 v207, 1.0, v207
	v_rcp_f32_e32 v180, v180
	v_rcp_f32_e32 v206, v206
	v_rcp_f32_e32 v207, v207
	v_rcp_f32_e32 v227, v227
	v_cvt_pk_bf16_f32 v180, v180, v206
	ds_bpermute_b32 v206, v226, v180
	v_cvt_pk_bf16_f32 v207, v207, v227
	ds_bpermute_b32 v207, v226, v207
	v_mul_f32_e32 v180, 0xbfb8aa3b, v12
	v_exp_f32_e32 v180, v180
	s_waitcnt lgkmcnt(0)
	global_store_dwordx2 v[208:209], v[206:207], off offset:288
	v_mul_f32_e32 v206, 0xbfb8aa3b, v13
	v_mul_f32_e32 v207, 0xbfb8aa3b, v14
	v_mul_f32_e32 v208, 0xbfb8aa3b, v15
	v_exp_f32_e32 v206, v206
	v_exp_f32_e32 v207, v207
	v_exp_f32_e32 v208, v208
	v_add_f32_e32 v180, 1.0, v180
	v_add_f32_e32 v206, 1.0, v206
	v_add_f32_e32 v207, 1.0, v207
	v_add_f32_e32 v208, 1.0, v208
	v_rcp_f32_e32 v180, v180
	v_rcp_f32_e32 v206, v206
	v_rcp_f32_e32 v207, v207
	v_rcp_f32_e32 v208, v208
	v_cvt_pk_bf16_f32 v180, v180, v206
	ds_bpermute_b32 v206, v226, v180
	v_cvt_pk_bf16_f32 v207, v207, v208
	ds_bpermute_b32 v207, v226, v207
	v_lshl_add_u64 v[208:209], v[130:131], 0, s[4:5]
	s_mov_b32 s4, 0xb0000
	v_add_co_u32_e32 v130, vcc, s4, v130
	v_mul_f32_e32 v180, 0xbfb8aa3b, v6
	s_nop 0
	v_addc_co_u32_e32 v131, vcc, 0, v131, vcc
	s_waitcnt lgkmcnt(0)
	global_store_dwordx2 v[130:131], v[206:207], off
	v_mul_f32_e32 v130, 0xbfb8aa3b, v4
	v_mul_f32_e32 v131, 0xbfb8aa3b, v5
	v_mul_f32_e32 v206, 0xbfb8aa3b, v7
	v_exp_f32_e32 v130, v130
	v_exp_f32_e32 v131, v131
	v_exp_f32_e32 v180, v180
	v_exp_f32_e32 v206, v206
	v_add_f32_e32 v130, 1.0, v130
	v_add_f32_e32 v131, 1.0, v131
	v_add_f32_e32 v180, 1.0, v180
	v_add_f32_e32 v206, 1.0, v206
	v_rcp_f32_e32 v130, v130
	v_rcp_f32_e32 v131, v131
	v_rcp_f32_e32 v180, v180
	v_rcp_f32_e32 v206, v206
	s_mov_b64 s[4:5], 0
	v_cvt_pk_bf16_f32 v130, v130, v131
	ds_bpermute_b32 v130, v226, v130
	v_cvt_pk_bf16_f32 v131, v180, v206
	ds_bpermute_b32 v131, v226, v131
	v_mul_f32_e32 v180, 0xbfb8aa3b, v10
	v_mul_f32_e32 v206, 0xbfb8aa3b, v11
	v_exp_f32_e32 v180, v180
	v_exp_f32_e32 v206, v206
	s_waitcnt lgkmcnt(0)
	global_store_dwordx2 v[208:209], v[130:131], off offset:32
	v_mul_f32_e32 v130, 0xbfb8aa3b, v8
	v_mul_f32_e32 v131, 0xbfb8aa3b, v9
	v_exp_f32_e32 v130, v130
	v_exp_f32_e32 v131, v131
	v_add_f32_e32 v180, 1.0, v180
	v_add_f32_e32 v206, 1.0, v206
	v_add_f32_e32 v130, 1.0, v130
	v_add_f32_e32 v131, 1.0, v131
	v_rcp_f32_e32 v130, v130
	v_rcp_f32_e32 v131, v131
	v_rcp_f32_e32 v180, v180
	v_rcp_f32_e32 v206, v206
	v_cvt_pk_bf16_f32 v130, v130, v131
	ds_bpermute_b32 v130, v226, v130
	v_cvt_pk_bf16_f32 v131, v180, v206
	ds_bpermute_b32 v131, v226, v131
	v_mul_f32_e32 v180, 0xbfb8aa3b, v2
	v_mul_f32_e32 v206, 0xbfb8aa3b, v3
	v_exp_f32_e32 v180, v180
	v_exp_f32_e32 v206, v206
	s_waitcnt lgkmcnt(0)
	global_store_dwordx2 v[208:209], v[130:131], off offset:256
	v_mul_f32_e32 v130, 0xbfb8aa3b, v0
	v_mul_f32_e32 v131, 0xbfb8aa3b, v1
	v_exp_f32_e32 v130, v130
	v_exp_f32_e32 v131, v131
	v_add_f32_e32 v180, 1.0, v180
	v_add_f32_e32 v206, 1.0, v206
	v_add_f32_e32 v130, 1.0, v130
	v_add_f32_e32 v131, 1.0, v131
	v_rcp_f32_e32 v130, v130
	v_rcp_f32_e32 v131, v131
	v_rcp_f32_e32 v180, v180
	v_rcp_f32_e32 v206, v206
	v_cvt_pk_bf16_f32 v130, v130, v131
	ds_bpermute_b32 v130, v226, v130
	v_cvt_pk_bf16_f32 v131, v180, v206
	ds_bpermute_b32 v131, v226, v131
	s_waitcnt lgkmcnt(0)
	global_store_dwordx2 v[208:209], v[130:131], off offset:288

.LBB0_1024:
	s_waitcnt lgkmcnt(0)
	ds_read_b128 v[128:131], v179
	ds_read_b128 v[132:135], v179 offset:1024
	ds_read_b128 v[136:139], v179 offset:2048
	ds_read_b128 v[140:143], v179 offset:3072
	s_add_i32 s62, s36, 2
	s_add_u32 s37, s4, 0xfff80080
	s_addc_u32 s38, s5, -1
	s_cmp_eq_u32 s59, s36
	s_cselect_b32 s36, s58, s60
	s_cselect_b32 s39, s21, s38
	s_cselect_b32 s38, s25, s37
	s_cselect_b32 s37, s23, s61
	v_lshl_add_u64 v[166:167], s[4:5], 0, v[162:163]
	s_add_i32 m0, s31, 0xc000
	ds_read_b128 v[144:147], v190
	ds_read_b128 v[148:151], v190 offset:1024
	ds_read_b128 v[152:155], v190 offset:2048
	ds_read_b128 v[156:159], v190 offset:3072
	ds_read_b128 v[180:183], v190 offset:4096
	ds_read_b128 v[184:187], v190 offset:5120
	ds_read_b128 v[194:197], v190 offset:6144
	ds_read_b128 v[198:201], v190 offset:7168
	global_load_lds_dwordx4 v[166:167], off
	s_add_i32 m0, s31, 0xe000
	s_nop 0

	global_load_lds_dwordx4 v164, s[4:5]
	s_waitcnt lgkmcnt(8)
	s_barrier
	s_waitcnt lgkmcnt(0)


	v_mfma_f32_16x16x32_bf16 v[124:127], v[128:131], v[144:147], v[124:127]
	v_mfma_f32_16x16x32_bf16 v[120:123], v[136:139], v[144:147], v[120:123]
	v_mfma_f32_16x16x32_bf16 v[116:119], v[128:131], v[152:155], v[116:119]
	v_mfma_f32_16x16x32_bf16 v[104:107], v[136:139], v[152:155], v[104:107]
	v_mfma_f32_16x16x32_bf16 v[96:99], v[128:131], v[180:183], v[96:99]
	v_mfma_f32_16x16x32_bf16 v[88:91], v[136:139], v[180:183], v[88:91]
	v_mfma_f32_16x16x32_bf16 v[80:83], v[128:131], v[194:197], v[80:83]
	v_mfma_f32_16x16x32_bf16 v[72:75], v[136:139], v[194:197], v[72:75]
	v_mfma_f32_16x16x32_bf16 v[124:127], v[132:135], v[148:151], v[124:127]
	v_mfma_f32_16x16x32_bf16 v[120:123], v[140:143], v[148:151], v[120:123]
	v_mfma_f32_16x16x32_bf16 v[116:119], v[132:135], v[156:159], v[116:119]
	v_mfma_f32_16x16x32_bf16 v[104:107], v[140:143], v[156:159], v[104:107]
	v_mfma_f32_16x16x32_bf16 v[96:99], v[132:135], v[184:187], v[96:99]
	v_mfma_f32_16x16x32_bf16 v[88:91], v[140:143], v[184:187], v[88:91]
	v_mfma_f32_16x16x32_bf16 v[80:83], v[132:135], v[198:201], v[80:83]
	v_mfma_f32_16x16x32_bf16 v[72:75], v[140:143], v[198:201], v[72:75]

	s_barrier
	s_add_i32 s63, s52, s42
	v_lshl_add_u64 v[166:167], s[36:37], 0, v[172:173]
	s_mov_b32 m0, s63
	ds_read_b128 v[202:205], v191
	ds_read_b128 v[206:209], v191 offset:1024
	ds_read_b128 v[222:225], v191 offset:2048
	ds_read_b128 v[226:229], v191 offset:3072
	global_load_lds_dwordx4 v[166:167], off
	s_add_i32 m0, s63, 0x2000
	v_lshl_add_u64 v[188:189], s[36:37], 0, v[174:175]

	global_load_lds_dwordx4 v[188:189], off
	s_barrier
	s_waitcnt lgkmcnt(0)


	v_mfma_f32_16x16x32_bf16 v[112:115], v[202:205], v[144:147], v[112:115]
	v_mfma_f32_16x16x32_bf16 v[108:111], v[222:225], v[144:147], v[108:111]
	v_mfma_f32_16x16x32_bf16 v[100:103], v[202:205], v[152:155], v[100:103]
	v_mfma_f32_16x16x32_bf16 v[92:95], v[222:225], v[152:155], v[92:95]
	v_mfma_f32_16x16x32_bf16 v[84:87], v[202:205], v[180:183], v[84:87]
	v_mfma_f32_16x16x32_bf16 v[76:79], v[222:225], v[180:183], v[76:79]
	v_mfma_f32_16x16x32_bf16 v[68:71], v[202:205], v[194:197], v[68:71]
	v_mfma_f32_16x16x32_bf16 v[64:67], v[222:225], v[194:197], v[64:67]
	v_mfma_f32_16x16x32_bf16 v[112:115], v[206:209], v[148:151], v[112:115]
	v_mfma_f32_16x16x32_bf16 v[108:111], v[226:229], v[148:151], v[108:111]
	v_mfma_f32_16x16x32_bf16 v[100:103], v[206:209], v[156:159], v[100:103]
	v_mfma_f32_16x16x32_bf16 v[92:95], v[226:229], v[156:159], v[92:95]
	v_mfma_f32_16x16x32_bf16 v[84:87], v[206:209], v[184:187], v[84:87]
	v_mfma_f32_16x16x32_bf16 v[76:79], v[226:229], v[184:187], v[76:79]
	v_mfma_f32_16x16x32_bf16 v[68:71], v[206:209], v[198:201], v[68:71]
	v_mfma_f32_16x16x32_bf16 v[64:67], v[226:229], v[198:201], v[64:67]

	s_mov_b32 m0, s31
	v_lshl_add_u64 v[230:231], s[38:39], 0, v[172:173]
	s_barrier
	ds_read_b128 v[144:147], v190 offset:16384
	ds_read_b128 v[148:151], v190 offset:17408
	ds_read_b128 v[152:155], v190 offset:18432
	ds_read_b128 v[156:159], v190 offset:19456
	ds_read_b128 v[180:183], v190 offset:20480
	ds_read_b128 v[184:187], v190 offset:21504
	ds_read_b128 v[194:197], v190 offset:22528
	ds_read_b128 v[198:201], v190 offset:23552
	global_load_lds_dwordx4 v[230:231], off
	s_mov_b32 m0, s35
	v_lshl_add_u64 v[232:233], s[38:39], 0, v[174:175]

	global_load_lds_dwordx4 v[232:233], off
	s_barrier
	s_waitcnt lgkmcnt(0)


	v_mfma_f32_16x16x32_bf16 v[60:63], v[128:131], v[144:147], v[60:63]
	v_mfma_f32_16x16x32_bf16 v[56:59], v[136:139], v[144:147], v[56:59]
	v_mfma_f32_16x16x32_bf16 v[52:55], v[128:131], v[152:155], v[52:55]
	v_mfma_f32_16x16x32_bf16 v[40:43], v[136:139], v[152:155], v[40:43]
	v_mfma_f32_16x16x32_bf16 v[36:39], v[128:131], v[180:183], v[36:39]
	v_mfma_f32_16x16x32_bf16 v[24:27], v[136:139], v[180:183], v[24:27]
	v_mfma_f32_16x16x32_bf16 v[20:23], v[128:131], v[194:197], v[20:23]
	v_mfma_f32_16x16x32_bf16 v[8:11], v[136:139], v[194:197], v[8:11]
	v_mfma_f32_16x16x32_bf16 v[60:63], v[132:135], v[148:151], v[60:63]
	v_mfma_f32_16x16x32_bf16 v[56:59], v[140:143], v[148:151], v[56:59]
	v_mfma_f32_16x16x32_bf16 v[52:55], v[132:135], v[156:159], v[52:55]
	v_mfma_f32_16x16x32_bf16 v[40:43], v[140:143], v[156:159], v[40:43]
	v_mfma_f32_16x16x32_bf16 v[36:39], v[132:135], v[184:187], v[36:39]
	v_mfma_f32_16x16x32_bf16 v[24:27], v[140:143], v[184:187], v[24:27]
	v_mfma_f32_16x16x32_bf16 v[20:23], v[132:135], v[198:201], v[20:23]
	v_mfma_f32_16x16x32_bf16 v[8:11], v[140:143], v[198:201], v[8:11]

	s_barrier
	s_add_u32 s64, s36, 0x80000
	s_addc_u32 s65, s37, 0
	s_add_i32 s63, s53, s42
	s_mov_b32 m0, s63
	s_nop 0

	global_load_lds_dwordx4 v172, s[64:65]
	s_add_i32 m0, s63, 0x2000
	s_nop 0

	global_load_lds_dwordx4 v174, s[64:65]
	s_waitcnt vmcnt(6)
	s_barrier

	v_mfma_f32_16x16x32_bf16 v[48:51], v[202:205], v[144:147], v[48:51]
	v_mfma_f32_16x16x32_bf16 v[44:47], v[222:225], v[144:147], v[44:47]
	v_mfma_f32_16x16x32_bf16 v[32:35], v[202:205], v[152:155], v[32:35]
	v_mfma_f32_16x16x32_bf16 v[28:31], v[222:225], v[152:155], v[28:31]
	v_mfma_f32_16x16x32_bf16 v[16:19], v[202:205], v[180:183], v[16:19]
	v_mfma_f32_16x16x32_bf16 v[12:15], v[222:225], v[180:183], v[12:15]
	v_mfma_f32_16x16x32_bf16 v[4:7], v[202:205], v[194:197], v[4:7]
	v_mfma_f32_16x16x32_bf16 v[0:3], v[222:225], v[194:197], v[0:3]
	v_mfma_f32_16x16x32_bf16 v[48:51], v[206:209], v[148:151], v[48:51]
	v_mfma_f32_16x16x32_bf16 v[44:47], v[226:229], v[148:151], v[44:47]
	v_mfma_f32_16x16x32_bf16 v[32:35], v[206:209], v[156:159], v[32:35]
	v_mfma_f32_16x16x32_bf16 v[28:31], v[226:229], v[156:159], v[28:31]
	v_mfma_f32_16x16x32_bf16 v[16:19], v[206:209], v[184:187], v[16:19]
	v_mfma_f32_16x16x32_bf16 v[12:15], v[226:229], v[184:187], v[12:15]
	v_mfma_f32_16x16x32_bf16 v[4:7], v[206:209], v[198:201], v[4:7]
	v_mfma_f32_16x16x32_bf16 v[0:3], v[226:229], v[198:201], v[0:3]

	s_add_i32 s63, 0, 0x18000
	v_add_u32_e32 v140, s63, v177
	s_barrier
	ds_read_b128 v[128:131], v140
	ds_read_b128 v[132:135], v140 offset:1024
	ds_read_b128 v[136:139], v140 offset:2048
	ds_read_b128 v[140:143], v140 offset:3072
	s_add_u32 s38, s38, 0x80000
	s_addc_u32 s39, s39, 0
	s_mov_b32 m0, s43
	v_lshl_add_u64 v[202:203], s[38:39], 0, v[172:173]
	ds_read_b128 v[144:147], v190 offset:32768
	ds_read_b128 v[148:151], v190 offset:33792
	ds_read_b128 v[152:155], v190 offset:34816
	ds_read_b128 v[156:159], v190 offset:35840
	ds_read_b128 v[180:183], v190 offset:36864
	ds_read_b128 v[184:187], v190 offset:37888
	ds_read_b128 v[194:197], v190 offset:38912
	ds_read_b128 v[198:201], v190 offset:39936
	global_load_lds_dwordx4 v[202:203], off
	s_mov_b32 m0, s44
	s_nop 0

	global_load_lds_dwordx4 v174, s[38:39]
	s_waitcnt lgkmcnt(8)
	s_barrier
	s_waitcnt lgkmcnt(0)


	v_mfma_f32_16x16x32_bf16 v[124:127], v[128:131], v[144:147], v[124:127]
	v_mfma_f32_16x16x32_bf16 v[120:123], v[136:139], v[144:147], v[120:123]
	v_mfma_f32_16x16x32_bf16 v[116:119], v[128:131], v[152:155], v[116:119]
	v_mfma_f32_16x16x32_bf16 v[104:107], v[136:139], v[152:155], v[104:107]
	v_mfma_f32_16x16x32_bf16 v[96:99], v[128:131], v[180:183], v[96:99]
	v_mfma_f32_16x16x32_bf16 v[88:91], v[136:139], v[180:183], v[88:91]
	v_mfma_f32_16x16x32_bf16 v[80:83], v[128:131], v[194:197], v[80:83]
	v_mfma_f32_16x16x32_bf16 v[72:75], v[136:139], v[194:197], v[72:75]
	v_mfma_f32_16x16x32_bf16 v[124:127], v[132:135], v[148:151], v[124:127]
	v_mfma_f32_16x16x32_bf16 v[120:123], v[140:143], v[148:151], v[120:123]
	v_mfma_f32_16x16x32_bf16 v[116:119], v[132:135], v[156:159], v[116:119]
	v_mfma_f32_16x16x32_bf16 v[104:107], v[140:143], v[156:159], v[104:107]
	v_mfma_f32_16x16x32_bf16 v[96:99], v[132:135], v[184:187], v[96:99]
	v_mfma_f32_16x16x32_bf16 v[88:91], v[140:143], v[184:187], v[88:91]
	v_mfma_f32_16x16x32_bf16 v[80:83], v[132:135], v[198:201], v[80:83]
	v_mfma_f32_16x16x32_bf16 v[72:75], v[140:143], v[198:201], v[72:75]

	s_barrier
	s_add_i32 s38, 0, 0x1c000
	s_add_i32 s39, s63, s42
	v_add_u32_e32 v160, s38, v177
	v_lshl_add_u64 v[166:167], v[166:167], 0, s[14:15]
	s_mov_b32 m0, s39
	ds_read_b128 v[202:205], v160
	ds_read_b128 v[206:209], v160 offset:1024
	ds_read_b128 v[222:225], v160 offset:2048
	ds_read_b128 v[226:229], v160 offset:3072
	global_load_lds_dwordx4 v[166:167], off
	s_add_i32 m0, s39, 0x2000
	v_lshl_add_u64 v[166:167], v[188:189], 0, s[14:15]

	global_load_lds_dwordx4 v[166:167], off
	s_barrier
	s_waitcnt lgkmcnt(0)


	v_mfma_f32_16x16x32_bf16 v[112:115], v[202:205], v[144:147], v[112:115]
	v_mfma_f32_16x16x32_bf16 v[108:111], v[222:225], v[144:147], v[108:111]
	v_mfma_f32_16x16x32_bf16 v[100:103], v[202:205], v[152:155], v[100:103]
	v_mfma_f32_16x16x32_bf16 v[92:95], v[222:225], v[152:155], v[92:95]
	v_mfma_f32_16x16x32_bf16 v[84:87], v[202:205], v[180:183], v[84:87]
	v_mfma_f32_16x16x32_bf16 v[76:79], v[222:225], v[180:183], v[76:79]
	v_mfma_f32_16x16x32_bf16 v[68:71], v[202:205], v[194:197], v[68:71]
	v_mfma_f32_16x16x32_bf16 v[64:67], v[222:225], v[194:197], v[64:67]
	v_mfma_f32_16x16x32_bf16 v[112:115], v[206:209], v[148:151], v[112:115]
	v_mfma_f32_16x16x32_bf16 v[108:111], v[226:229], v[148:151], v[108:111]
	v_mfma_f32_16x16x32_bf16 v[100:103], v[206:209], v[156:159], v[100:103]
	v_mfma_f32_16x16x32_bf16 v[92:95], v[226:229], v[156:159], v[92:95]
	v_mfma_f32_16x16x32_bf16 v[84:87], v[206:209], v[184:187], v[84:87]
	v_mfma_f32_16x16x32_bf16 v[76:79], v[226:229], v[184:187], v[76:79]
	v_mfma_f32_16x16x32_bf16 v[68:71], v[206:209], v[198:201], v[68:71]
	v_mfma_f32_16x16x32_bf16 v[64:67], v[226:229], v[198:201], v[64:67]

	s_mov_b32 m0, s48
	v_lshl_add_u64 v[166:167], v[230:231], 0, s[14:15]
	s_barrier
	ds_read_b128 v[144:147], v190 offset:49152
	ds_read_b128 v[148:151], v190 offset:50176
	ds_read_b128 v[152:155], v190 offset:51200
	ds_read_b128 v[156:159], v190 offset:52224
	ds_read_b128 v[180:183], v190 offset:53248
	ds_read_b128 v[184:187], v190 offset:54272
	ds_read_b128 v[194:197], v190 offset:55296
	ds_read_b128 v[198:201], v190 offset:56320
	global_load_lds_dwordx4 v[166:167], off
	s_mov_b32 m0, s49
	v_lshl_add_u64 v[166:167], v[232:233], 0, s[14:15]

	global_load_lds_dwordx4 v[166:167], off
	s_barrier
	s_waitcnt lgkmcnt(0)


	v_mfma_f32_16x16x32_bf16 v[60:63], v[128:131], v[144:147], v[60:63]
	v_mfma_f32_16x16x32_bf16 v[56:59], v[136:139], v[144:147], v[56:59]
	v_mfma_f32_16x16x32_bf16 v[52:55], v[128:131], v[152:155], v[52:55]
	v_mfma_f32_16x16x32_bf16 v[40:43], v[136:139], v[152:155], v[40:43]
	v_mfma_f32_16x16x32_bf16 v[36:39], v[128:131], v[180:183], v[36:39]
	v_mfma_f32_16x16x32_bf16 v[24:27], v[136:139], v[180:183], v[24:27]
	v_mfma_f32_16x16x32_bf16 v[20:23], v[128:131], v[194:197], v[20:23]
	v_mfma_f32_16x16x32_bf16 v[8:11], v[136:139], v[194:197], v[8:11]
	v_mfma_f32_16x16x32_bf16 v[60:63], v[132:135], v[148:151], v[60:63]
	v_mfma_f32_16x16x32_bf16 v[56:59], v[140:143], v[148:151], v[56:59]
	v_mfma_f32_16x16x32_bf16 v[52:55], v[132:135], v[156:159], v[52:55]
	v_mfma_f32_16x16x32_bf16 v[40:43], v[140:143], v[156:159], v[40:43]
	v_mfma_f32_16x16x32_bf16 v[36:39], v[132:135], v[184:187], v[36:39]
	v_mfma_f32_16x16x32_bf16 v[24:27], v[140:143], v[184:187], v[24:27]
	v_mfma_f32_16x16x32_bf16 v[20:23], v[132:135], v[198:201], v[20:23]
	v_mfma_f32_16x16x32_bf16 v[8:11], v[140:143], v[198:201], v[8:11]

	s_barrier
	s_add_u32 s36, s36, 0x80080
	s_addc_u32 s37, s37, 0
	s_add_i32 s38, s38, s42
	s_mov_b32 m0, s38
	s_nop 0

	global_load_lds_dwordx4 v172, s[36:37]
	s_add_i32 m0, s38, 0x2000
	s_nop 0

	global_load_lds_dwordx4 v174, s[36:37]
	s_waitcnt vmcnt(6)
	s_barrier

	v_mfma_f32_16x16x32_bf16 v[48:51], v[202:205], v[144:147], v[48:51]
	v_mfma_f32_16x16x32_bf16 v[44:47], v[222:225], v[144:147], v[44:47]
	v_mfma_f32_16x16x32_bf16 v[32:35], v[202:205], v[152:155], v[32:35]
	v_mfma_f32_16x16x32_bf16 v[28:31], v[222:225], v[152:155], v[28:31]
	v_mfma_f32_16x16x32_bf16 v[16:19], v[202:205], v[180:183], v[16:19]
	v_mfma_f32_16x16x32_bf16 v[12:15], v[222:225], v[180:183], v[12:15]
	v_mfma_f32_16x16x32_bf16 v[4:7], v[202:205], v[194:197], v[4:7]
	v_mfma_f32_16x16x32_bf16 v[0:3], v[222:225], v[194:197], v[0:3]
	v_mfma_f32_16x16x32_bf16 v[48:51], v[206:209], v[148:151], v[48:51]
	v_mfma_f32_16x16x32_bf16 v[44:47], v[226:229], v[148:151], v[44:47]
	v_mfma_f32_16x16x32_bf16 v[32:35], v[206:209], v[156:159], v[32:35]
	v_mfma_f32_16x16x32_bf16 v[28:31], v[226:229], v[156:159], v[28:31]
	v_mfma_f32_16x16x32_bf16 v[16:19], v[206:209], v[184:187], v[16:19]
	v_mfma_f32_16x16x32_bf16 v[12:15], v[226:229], v[184:187], v[12:15]
	v_mfma_f32_16x16x32_bf16 v[4:7], v[206:209], v[198:201], v[4:7]
	v_mfma_f32_16x16x32_bf16 v[0:3], v[226:229], v[198:201], v[0:3]

	s_add_u32 s4, s4, 0x100
	s_addc_u32 s5, s5, 0
	s_add_u32 s60, s60, 0x100
	s_addc_u32 s61, s61, 0
	s_cmp_ge_i32 s62, s17
	s_mov_b32 s36, s62
	s_barrier
	s_cbranch_scc0 .LBB0_1024
	v_mov_b32_e32 v128, v210
	v_mov_b32_e32 v129, v169
	s_cmp_lt_i32 s12, 0
	v_lshl_add_u32 v128, v128, 4, v129
	v_ashrrev_i32_e32 v166, 2, v128
	v_and_b32_e32 v160, 3, v129
	v_and_b32_e32 v128, -4, v128
	v_lshl_add_u32 v193, v160, 6, v128
	s_mov_b64 s[4:5], -1
	s_cbranch_scc0 .LBB0_1043
	s_lshl_b32 s4, s30, 8
	v_lshl_or_b32 v128, v160, 2, s4
	s_lshl_b32 s4, s34, 8
	v_or_b32_e32 v180, s47, v128
	s_add_i32 s4, s4, s46
	v_readlane_b32 s60, v254, 6
	v_ashrrev_i32_e32 v181, 31, v180
	v_add_u32_e32 v184, s4, v166
	s_cmp_lt_i32 s34, 32
	v_readlane_b32 s61, v254, 7
	v_lshlrev_b64 v[128:129], 2, v[180:181]
	v_readlane_b32 s62, v254, 8
	v_readlane_b32 s63, v254, 9
	v_readlane_b32 s64, v254, 10
	v_readlane_b32 s65, v254, 11
	v_readlane_b32 s66, v254, 12
	v_readlane_b32 s67, v254, 13
	v_readlane_b32 s68, v254, 14
	v_readlane_b32 s69, v254, 15
	v_readlane_b32 s70, v254, 16
	v_readlane_b32 s71, v254, 17
	v_readlane_b32 s72, v254, 18
	v_readlane_b32 s73, v254, 19
	v_readlane_b32 s74, v254, 20
	v_readlane_b32 s75, v254, 21
	s_cselect_b32 s5, s61, s51
	s_cselect_b32 s4, s60, s50
	v_ashrrev_i32_e32 v185, 31, v184
	v_lshl_add_u64 v[182:183], s[4:5], 0, v[128:129]
	v_lshlrev_b64 v[130:131], 13, v[184:185]
	v_readlane_b32 s60, v254, 22
	v_lshl_add_u64 v[136:137], v[182:183], 0, v[130:131]
	v_readlane_b32 s61, v254, 23
	v_readlane_b32 s68, v254, 30
	v_readlane_b32 s69, v254, 31
	global_load_dwordx4 v[196:199], v[136:137], off nt
	global_load_dwordx4 v[200:203], v[136:137], off offset:64 nt
	global_load_dwordx4 v[204:207], v[136:137], off offset:512 nt
	s_mov_b64 s[60:61], s[68:69]
	v_lshl_add_u64 v[138:139], s[60:61], 0, v[128:129]
	global_load_dwordx4 v[140:143], v[138:139], off
	global_load_dwordx4 v[132:135], v[138:139], off offset:64
	global_load_dwordx4 v[128:131], v[138:139], off offset:512
	global_load_dwordx4 v[222:225], v[136:137], off offset:576 nt
	v_and_b32_e32 v145, 64, v192
	global_load_dwordx4 v[136:139], v[138:139], off offset:576
	v_xor_b32_e32 v144, 1, v192
	v_add_u32_e32 v194, 64, v145
	v_add_u32_e32 v186, 16, v184
	v_cmp_lt_i32_e64 s[4:5], v144, v194
	v_ashrrev_i32_e32 v187, 31, v186
	ds_bpermute_b32 v188, v193, v124
	v_cndmask_b32_e64 v195, v192, v144, s[4:5]
	v_lshlrev_b64 v[144:145], 13, v[186:187]
	v_lshl_add_u64 v[144:145], v[182:183], 0, v[144:145]
	global_load_dwordx4 v[156:159], v[144:145], off nt
	global_load_dwordx4 v[152:155], v[144:145], off offset:64 nt
	global_load_dwordx4 v[148:151], v[144:145], off offset:512 nt
	s_nop 0
	global_load_dwordx4 v[144:147], v[144:145], off offset:576 nt
	ds_bpermute_b32 v189, v193, v125
	ds_bpermute_b32 v208, v193, v126
	ds_bpermute_b32 v209, v193, v127
	ds_bpermute_b32 v226, v193, v120
	ds_bpermute_b32 v227, v193, v121
	ds_bpermute_b32 v228, v193, v122
	ds_bpermute_b32 v229, v193, v123
	ds_bpermute_b32 v230, v193, v112
	ds_bpermute_b32 v231, v193, v113
	v_readlane_b32 s64, v254, 26
	v_readlane_b32 s65, v254, 27
	v_readlane_b32 s66, v254, 28
	v_readlane_b32 s67, v254, 29
	v_readlane_b32 s72, v254, 34
	v_readlane_b32 s73, v254, 35
	v_readlane_b32 s74, v254, 36
	v_readlane_b32 s75, v254, 37
	s_mov_b64 s[64:65], s[72:73]
	ds_bpermute_b32 v232, v193, v114
	ds_bpermute_b32 v233, v193, v115
	v_lshlrev_b64 v[234:235], 11, v[184:185]
	s_mov_b64 s[66:67], s[74:75]
	v_lshl_add_u64 v[234:235], v[234:235], 0, v[180:181]
	v_xor_b32_e32 v167, 2, v192
	v_lshl_add_u64 v[236:237], v[234:235], 2, s[66:67]
	v_readlane_b32 s2, v254, 54
	v_cmp_lt_i32_e64 s[4:5], v167, v194
	v_lshlrev_b32_e32 v194, 2, v195
	v_lshlrev_b64 v[234:235], 1, v[234:235]
	v_readlane_b32 s3, v254, 55
	v_or_b32_e32 v240, 32, v234
	v_mov_b32_e32 v241, v235
	v_lshl_add_u64 v[238:239], s[2:3], 0, v[234:235]
	v_lshl_add_u64 v[240:241], s[2:3], 0, v[240:241]
	v_cndmask_b32_e64 v167, v192, v167, s[4:5]
	v_lshlrev_b32_e32 v167, 2, v167
	v_cmp_eq_u32_e32 vcc, 0, v160
	v_readlane_b32 s62, v254, 24
	v_readlane_b32 s63, v254, 25
	v_readlane_b32 s70, v254, 32
	v_readlane_b32 s71, v254, 33
	s_waitcnt vmcnt(0) lgkmcnt(0)
	v_pk_add_f32 v[198:199], v[198:199], v[208:209]
	v_pk_add_f32 v[196:197], v[196:197], v[188:189]
	v_pk_add_f32 v[202:203], v[202:203], v[228:229]
	v_pk_add_f32 v[200:201], v[200:201], v[226:227]
	v_pk_add_f32 v[204:205], v[204:205], v[230:231]
	v_mul_f32_e32 v195, v197, v197
	v_mul_f32_e32 v221, v199, v199
	global_store_dwordx4 v[236:237], v[196:199], off
	v_pk_mul_f32 v[188:189], v[142:143], v[198:199]
	v_pk_mul_f32 v[208:209], v[140:141], v[196:197]
	v_mul_f32_e32 v199, v201, v201
	v_mul_f32_e32 v230, v203, v203
	v_pk_mul_f32 v[226:227], v[134:135], v[202:203]
	v_pk_mul_f32 v[228:229], v[132:133], v[200:201]
	v_fmac_f32_e32 v195, v196, v196
	v_fmac_f32_e32 v221, v198, v198
	v_cvt_pk_bf16_f32 v196, v208, v209
	v_cvt_pk_bf16_f32 v197, v188, v189
	v_fmac_f32_e32 v199, v200, v200
	v_fmac_f32_e32 v230, v202, v202
	v_pk_add_f32 v[206:207], v[206:207], v[232:233]
	v_cvt_pk_bf16_f32 v188, v228, v229
	v_cvt_pk_bf16_f32 v189, v226, v227
	v_add_f32_e32 v195, v195, v221
	global_store_dwordx2 v[238:239], v[196:197], off
	v_add_f32_e32 v196, v199, v230
	global_store_dwordx4 v[236:237], v[200:203], off offset:64
	global_store_dwordx2 v[240:241], v[188:189], off
	v_add_f32_e32 v188, v195, v196
	v_mul_f32_e32 v189, v205, v205
	v_mul_f32_e32 v195, v207, v207
	v_fmac_f32_e32 v189, v204, v204
	v_fmac_f32_e32 v195, v206, v206
	ds_bpermute_b32 v200, v193, v108
	ds_bpermute_b32 v198, v193, v110
	ds_bpermute_b32 v199, v193, v111
	ds_bpermute_b32 v201, v193, v109
	v_add_f32_e32 v189, v189, v195
	v_add_f32_e32 v195, v188, v189
	v_pk_mul_f32 v[188:189], v[130:131], v[206:207]
	v_pk_mul_f32 v[196:197], v[128:129], v[204:205]
	global_store_dwordx4 v[236:237], v[204:207], off offset:512
	v_cvt_pk_bf16_f32 v196, v196, v197
	v_cvt_pk_bf16_f32 v197, v188, v189
	v_or_b32_e32 v188, 0x100, v234
	v_mov_b32_e32 v189, v235
	v_lshl_add_u64 v[188:189], s[2:3], 0, v[188:189]
	global_store_dwordx2 v[188:189], v[196:197], off
	s_waitcnt lgkmcnt(1)
	v_pk_add_f32 v[198:199], v[224:225], v[198:199]
	s_waitcnt lgkmcnt(0)
	v_pk_add_f32 v[196:197], v[222:223], v[200:201]
	v_mul_f32_e32 v189, v199, v199
	v_mul_f32_e32 v188, v197, v197
	v_fmac_f32_e32 v188, v196, v196
	v_fmac_f32_e32 v189, v198, v198
	v_add_f32_e32 v188, v188, v189
	v_add_f32_e32 v195, v195, v188
	ds_bpermute_b32 v200, v194, v195
	v_pk_mul_f32 v[188:189], v[136:137], v[196:197]
	global_store_dwordx4 v[236:237], v[196:199], off offset:576
	v_or_b32_e32 v234, 0x120, v234
	s_nop 0
	v_cvt_pk_bf16_f32 v196, v188, v189
	s_waitcnt lgkmcnt(0)
	v_add_f32_e32 v188, v195, v200
	ds_bpermute_b32 v189, v167, v188
	v_pk_mul_f32 v[198:199], v[138:139], v[198:199]
	s_nop 0
	v_cvt_pk_bf16_f32 v197, v198, v199
	v_lshl_add_u64 v[198:199], s[2:3], 0, v[234:235]
	global_store_dwordx2 v[198:199], v[196:197], off
	s_and_saveexec_b64 s[4:5], vcc
	s_cbranch_execz .LBB0_1028
	s_waitcnt lgkmcnt(0)
	v_add_f32_e32 v195, v188, v189
	s_lshl_b32 s36, s30, 2
	v_lshlrev_b64 v[188:189], 7, v[184:185]
	s_ashr_i32 s37, s36, 31
	v_lshl_add_u64 v[188:189], s[10:11], 0, v[188:189]
	v_lshl_add_u64 v[188:189], s[36:37], 2, v[188:189]
	s_lshl_b32 s36, s45, 2
	s_mov_b32 s37, s13
	v_lshl_add_u64 v[188:189], v[188:189], 0, s[36:37]
	global_store_dword v[188:189], v195, off

.LBB0_1167:
	ds_read_b128 v[148:151], v143
	ds_read_b128 v[152:155], v143 offset:1024
	ds_read_b128 v[156:159], v143 offset:2048
	ds_read_b128 v[160:163], v143 offset:3072
	s_add_u32 s24, s22, 0xfff80080
	s_addc_u32 s25, s23, -1
	s_cmp_eq_u32 s53, 28
	s_cselect_b32 s27, s15, s25
	s_cselect_b32 s26, s49, s24
	s_cselect_b32 s25, s13, s52
	s_cselect_b32 s24, s50, s51
	v_lshl_add_u64 v[136:137], s[22:23], 0, v[128:129]
	s_add_i32 m0, s21, 0xc000
	ds_read_b128 v[164:167], v145
	ds_read_b128 v[176:179], v145 offset:1024
	ds_read_b128 v[180:183], v145 offset:2048
	ds_read_b128 v[184:187], v145 offset:3072
	ds_read_b128 v[188:191], v145 offset:4096
	ds_read_b128 v[192:195], v145 offset:5120
	ds_read_b128 v[196:199], v145 offset:6144
	ds_read_b128 v[200:203], v145 offset:7168
	global_load_lds_dwordx4 v[136:137], off
	s_add_i32 m0, s21, 0xe000
	s_nop 0

	global_load_lds_dwordx4 v130, s[22:23]
	s_waitcnt lgkmcnt(8)
	s_barrier
	s_waitcnt lgkmcnt(0)


	v_mfma_f32_16x16x32_bf16 v[124:127], v[148:151], v[164:167], v[124:127]
	v_mfma_f32_16x16x32_bf16 v[120:123], v[156:159], v[164:167], v[120:123]
	v_mfma_f32_16x16x32_bf16 v[116:119], v[148:151], v[180:183], v[116:119]
	v_mfma_f32_16x16x32_bf16 v[104:107], v[156:159], v[180:183], v[104:107]
	v_mfma_f32_16x16x32_bf16 v[96:99], v[148:151], v[188:191], v[96:99]
	v_mfma_f32_16x16x32_bf16 v[88:91], v[156:159], v[188:191], v[88:91]
	v_mfma_f32_16x16x32_bf16 v[80:83], v[148:151], v[196:199], v[80:83]
	v_mfma_f32_16x16x32_bf16 v[72:75], v[156:159], v[196:199], v[72:75]
	v_mfma_f32_16x16x32_bf16 v[124:127], v[152:155], v[176:179], v[124:127]
	v_mfma_f32_16x16x32_bf16 v[120:123], v[160:163], v[176:179], v[120:123]
	v_mfma_f32_16x16x32_bf16 v[116:119], v[152:155], v[184:187], v[116:119]
	v_mfma_f32_16x16x32_bf16 v[104:107], v[160:163], v[184:187], v[104:107]
	v_mfma_f32_16x16x32_bf16 v[96:99], v[152:155], v[192:195], v[96:99]
	v_mfma_f32_16x16x32_bf16 v[88:91], v[160:163], v[192:195], v[88:91]
	v_mfma_f32_16x16x32_bf16 v[80:83], v[152:155], v[200:203], v[80:83]
	v_mfma_f32_16x16x32_bf16 v[72:75], v[160:163], v[200:203], v[72:75]

	s_barrier
	s_add_i32 s54, s45, s31
	v_lshl_add_u64 v[136:137], s[24:25], 0, v[172:173]
	s_mov_b32 m0, s54
	ds_read_b128 v[204:207], v147
	ds_read_b128 v[218:221], v147 offset:1024
	ds_read_b128 v[222:225], v147 offset:2048
	ds_read_b128 v[226:229], v147 offset:3072
	global_load_lds_dwordx4 v[136:137], off
	s_add_i32 m0, s54, 0x2000
	v_lshl_add_u64 v[140:141], s[24:25], 0, v[174:175]

	global_load_lds_dwordx4 v[140:141], off
	s_barrier
	s_waitcnt lgkmcnt(0)


	v_mfma_f32_16x16x32_bf16 v[112:115], v[204:207], v[164:167], v[112:115]
	v_mfma_f32_16x16x32_bf16 v[108:111], v[222:225], v[164:167], v[108:111]
	v_mfma_f32_16x16x32_bf16 v[100:103], v[204:207], v[180:183], v[100:103]
	v_mfma_f32_16x16x32_bf16 v[92:95], v[222:225], v[180:183], v[92:95]
	v_mfma_f32_16x16x32_bf16 v[84:87], v[204:207], v[188:191], v[84:87]
	v_mfma_f32_16x16x32_bf16 v[76:79], v[222:225], v[188:191], v[76:79]
	v_mfma_f32_16x16x32_bf16 v[68:71], v[204:207], v[196:199], v[68:71]
	v_mfma_f32_16x16x32_bf16 v[64:67], v[222:225], v[196:199], v[64:67]
	v_mfma_f32_16x16x32_bf16 v[112:115], v[218:221], v[176:179], v[112:115]
	v_mfma_f32_16x16x32_bf16 v[108:111], v[226:229], v[176:179], v[108:111]
	v_mfma_f32_16x16x32_bf16 v[100:103], v[218:221], v[184:187], v[100:103]
	v_mfma_f32_16x16x32_bf16 v[92:95], v[226:229], v[184:187], v[92:95]
	v_mfma_f32_16x16x32_bf16 v[84:87], v[218:221], v[192:195], v[84:87]
	v_mfma_f32_16x16x32_bf16 v[76:79], v[226:229], v[192:195], v[76:79]
	v_mfma_f32_16x16x32_bf16 v[68:71], v[218:221], v[200:203], v[68:71]
	v_mfma_f32_16x16x32_bf16 v[64:67], v[226:229], v[200:203], v[64:67]

	s_mov_b32 m0, s21
	v_lshl_add_u64 v[208:209], s[26:27], 0, v[172:173]
	s_barrier
	ds_read_b128 v[164:167], v145 offset:16384
	ds_read_b128 v[176:179], v145 offset:17408
	ds_read_b128 v[180:183], v145 offset:18432
	ds_read_b128 v[184:187], v145 offset:19456
	ds_read_b128 v[188:191], v145 offset:20480
	ds_read_b128 v[192:195], v145 offset:21504
	ds_read_b128 v[196:199], v145 offset:22528
	ds_read_b128 v[200:203], v145 offset:23552
	global_load_lds_dwordx4 v[208:209], off
	s_mov_b32 m0, s35
	v_lshl_add_u64 v[230:231], s[26:27], 0, v[174:175]

	global_load_lds_dwordx4 v[230:231], off
	s_barrier
	s_waitcnt lgkmcnt(0)


	v_mfma_f32_16x16x32_bf16 v[60:63], v[148:151], v[164:167], v[60:63]
	v_mfma_f32_16x16x32_bf16 v[56:59], v[156:159], v[164:167], v[56:59]
	v_mfma_f32_16x16x32_bf16 v[48:51], v[148:151], v[180:183], v[48:51]
	v_mfma_f32_16x16x32_bf16 v[40:43], v[156:159], v[180:183], v[40:43]
	v_mfma_f32_16x16x32_bf16 v[32:35], v[148:151], v[188:191], v[32:35]
	v_mfma_f32_16x16x32_bf16 v[24:27], v[156:159], v[188:191], v[24:27]
	v_mfma_f32_16x16x32_bf16 v[16:19], v[148:151], v[196:199], v[16:19]
	v_mfma_f32_16x16x32_bf16 v[8:11], v[156:159], v[196:199], v[8:11]
	v_mfma_f32_16x16x32_bf16 v[60:63], v[152:155], v[176:179], v[60:63]
	v_mfma_f32_16x16x32_bf16 v[56:59], v[160:163], v[176:179], v[56:59]
	v_mfma_f32_16x16x32_bf16 v[48:51], v[152:155], v[184:187], v[48:51]
	v_mfma_f32_16x16x32_bf16 v[40:43], v[160:163], v[184:187], v[40:43]
	v_mfma_f32_16x16x32_bf16 v[32:35], v[152:155], v[192:195], v[32:35]
	v_mfma_f32_16x16x32_bf16 v[24:27], v[160:163], v[192:195], v[24:27]
	v_mfma_f32_16x16x32_bf16 v[16:19], v[152:155], v[200:203], v[16:19]
	v_mfma_f32_16x16x32_bf16 v[8:11], v[160:163], v[200:203], v[8:11]

	s_barrier
	s_add_u32 s54, s24, 0x80000
	s_addc_u32 s55, s25, 0
	s_add_i32 s56, s46, s31
	s_mov_b32 m0, s56
	s_nop 0

	global_load_lds_dwordx4 v172, s[54:55]
	s_add_i32 m0, s56, 0x2000
	s_nop 0

	global_load_lds_dwordx4 v174, s[54:55]
	s_waitcnt vmcnt(6)
	s_barrier

	v_mfma_f32_16x16x32_bf16 v[52:55], v[204:207], v[164:167], v[52:55]
	v_mfma_f32_16x16x32_bf16 v[44:47], v[222:225], v[164:167], v[44:47]
	v_mfma_f32_16x16x32_bf16 v[36:39], v[204:207], v[180:183], v[36:39]
	v_mfma_f32_16x16x32_bf16 v[28:31], v[222:225], v[180:183], v[28:31]
	v_mfma_f32_16x16x32_bf16 v[20:23], v[204:207], v[188:191], v[20:23]
	v_mfma_f32_16x16x32_bf16 v[12:15], v[222:225], v[188:191], v[12:15]
	v_mfma_f32_16x16x32_bf16 v[4:7], v[204:207], v[196:199], v[4:7]
	v_mfma_f32_16x16x32_bf16 v[0:3], v[222:225], v[196:199], v[0:3]
	v_mfma_f32_16x16x32_bf16 v[52:55], v[218:221], v[176:179], v[52:55]
	v_mfma_f32_16x16x32_bf16 v[44:47], v[226:229], v[176:179], v[44:47]
	v_mfma_f32_16x16x32_bf16 v[36:39], v[218:221], v[184:187], v[36:39]
	v_mfma_f32_16x16x32_bf16 v[28:31], v[226:229], v[184:187], v[28:31]
	v_mfma_f32_16x16x32_bf16 v[20:23], v[218:221], v[192:195], v[20:23]
	v_mfma_f32_16x16x32_bf16 v[12:15], v[226:229], v[192:195], v[12:15]
	v_mfma_f32_16x16x32_bf16 v[4:7], v[218:221], v[200:203], v[4:7]
	v_mfma_f32_16x16x32_bf16 v[0:3], v[226:229], v[200:203], v[0:3]

	s_add_i32 s54, 0, 0x18000
	v_add_u32_e32 v138, s54, v139
	s_barrier
	ds_read_b128 v[148:151], v138
	ds_read_b128 v[152:155], v138 offset:1024
	ds_read_b128 v[156:159], v138 offset:2048
	ds_read_b128 v[160:163], v138 offset:3072
	s_add_u32 s26, s26, 0x80000
	s_addc_u32 s27, s27, 0
	s_mov_b32 m0, s36
	v_lshl_add_u64 v[204:205], s[26:27], 0, v[172:173]
	ds_read_b128 v[164:167], v145 offset:32768
	ds_read_b128 v[176:179], v145 offset:33792
	ds_read_b128 v[180:183], v145 offset:34816
	ds_read_b128 v[184:187], v145 offset:35840
	ds_read_b128 v[188:191], v145 offset:36864
	ds_read_b128 v[192:195], v145 offset:37888
	ds_read_b128 v[196:199], v145 offset:38912
	ds_read_b128 v[200:203], v145 offset:39936
	global_load_lds_dwordx4 v[204:205], off
	s_mov_b32 m0, s37
	s_nop 0

	global_load_lds_dwordx4 v174, s[26:27]
	s_waitcnt lgkmcnt(8)
	s_barrier
	s_waitcnt lgkmcnt(0)


	v_mfma_f32_16x16x32_bf16 v[124:127], v[148:151], v[164:167], v[124:127]
	v_mfma_f32_16x16x32_bf16 v[120:123], v[156:159], v[164:167], v[120:123]
	v_mfma_f32_16x16x32_bf16 v[116:119], v[148:151], v[180:183], v[116:119]
	v_mfma_f32_16x16x32_bf16 v[104:107], v[156:159], v[180:183], v[104:107]
	v_mfma_f32_16x16x32_bf16 v[96:99], v[148:151], v[188:191], v[96:99]
	v_mfma_f32_16x16x32_bf16 v[88:91], v[156:159], v[188:191], v[88:91]
	v_mfma_f32_16x16x32_bf16 v[80:83], v[148:151], v[196:199], v[80:83]
	v_mfma_f32_16x16x32_bf16 v[72:75], v[156:159], v[196:199], v[72:75]
	v_mfma_f32_16x16x32_bf16 v[124:127], v[152:155], v[176:179], v[124:127]
	v_mfma_f32_16x16x32_bf16 v[120:123], v[160:163], v[176:179], v[120:123]
	v_mfma_f32_16x16x32_bf16 v[116:119], v[152:155], v[184:187], v[116:119]
	v_mfma_f32_16x16x32_bf16 v[104:107], v[160:163], v[184:187], v[104:107]
	v_mfma_f32_16x16x32_bf16 v[96:99], v[152:155], v[192:195], v[96:99]
	v_mfma_f32_16x16x32_bf16 v[88:91], v[160:163], v[192:195], v[88:91]
	v_mfma_f32_16x16x32_bf16 v[80:83], v[152:155], v[200:203], v[80:83]
	v_mfma_f32_16x16x32_bf16 v[72:75], v[160:163], v[200:203], v[72:75]

	s_barrier
	s_add_i32 s26, 0, 0x1c000
	s_add_i32 s27, s54, s31
	v_add_u32_e32 v138, s26, v139
	v_lshl_add_u64 v[136:137], v[136:137], 0, s[10:11]
	s_mov_b32 m0, s27
	ds_read_b128 v[204:207], v138
	ds_read_b128 v[218:221], v138 offset:1024
	ds_read_b128 v[222:225], v138 offset:2048
	ds_read_b128 v[226:229], v138 offset:3072
	global_load_lds_dwordx4 v[136:137], off
	s_add_i32 m0, s27, 0x2000
	v_lshl_add_u64 v[136:137], v[140:141], 0, s[10:11]

	global_load_lds_dwordx4 v[136:137], off
	s_barrier
	s_waitcnt lgkmcnt(0)


	v_mfma_f32_16x16x32_bf16 v[112:115], v[204:207], v[164:167], v[112:115]
	v_mfma_f32_16x16x32_bf16 v[108:111], v[222:225], v[164:167], v[108:111]
	v_mfma_f32_16x16x32_bf16 v[100:103], v[204:207], v[180:183], v[100:103]
	v_mfma_f32_16x16x32_bf16 v[92:95], v[222:225], v[180:183], v[92:95]
	v_mfma_f32_16x16x32_bf16 v[84:87], v[204:207], v[188:191], v[84:87]
	v_mfma_f32_16x16x32_bf16 v[76:79], v[222:225], v[188:191], v[76:79]
	v_mfma_f32_16x16x32_bf16 v[68:71], v[204:207], v[196:199], v[68:71]
	v_mfma_f32_16x16x32_bf16 v[64:67], v[222:225], v[196:199], v[64:67]
	v_mfma_f32_16x16x32_bf16 v[112:115], v[218:221], v[176:179], v[112:115]
	v_mfma_f32_16x16x32_bf16 v[108:111], v[226:229], v[176:179], v[108:111]
	v_mfma_f32_16x16x32_bf16 v[100:103], v[218:221], v[184:187], v[100:103]
	v_mfma_f32_16x16x32_bf16 v[92:95], v[226:229], v[184:187], v[92:95]
	v_mfma_f32_16x16x32_bf16 v[84:87], v[218:221], v[192:195], v[84:87]
	v_mfma_f32_16x16x32_bf16 v[76:79], v[226:229], v[192:195], v[76:79]
	v_mfma_f32_16x16x32_bf16 v[68:71], v[218:221], v[200:203], v[68:71]
	v_mfma_f32_16x16x32_bf16 v[64:67], v[226:229], v[200:203], v[64:67]

	s_mov_b32 m0, s41
	v_lshl_add_u64 v[136:137], v[208:209], 0, s[10:11]
	s_barrier
	ds_read_b128 v[164:167], v145 offset:49152
	ds_read_b128 v[176:179], v145 offset:50176
	ds_read_b128 v[180:183], v145 offset:51200
	ds_read_b128 v[184:187], v145 offset:52224
	ds_read_b128 v[188:191], v145 offset:53248
	ds_read_b128 v[192:195], v145 offset:54272
	ds_read_b128 v[196:199], v145 offset:55296
	ds_read_b128 v[200:203], v145 offset:56320
	global_load_lds_dwordx4 v[136:137], off
	s_mov_b32 m0, s42
	v_lshl_add_u64 v[136:137], v[230:231], 0, s[10:11]

	global_load_lds_dwordx4 v[136:137], off
	s_barrier
	s_waitcnt lgkmcnt(0)


	v_mfma_f32_16x16x32_bf16 v[60:63], v[148:151], v[164:167], v[60:63]
	v_mfma_f32_16x16x32_bf16 v[56:59], v[156:159], v[164:167], v[56:59]
	v_mfma_f32_16x16x32_bf16 v[48:51], v[148:151], v[180:183], v[48:51]
	v_mfma_f32_16x16x32_bf16 v[40:43], v[156:159], v[180:183], v[40:43]
	v_mfma_f32_16x16x32_bf16 v[32:35], v[148:151], v[188:191], v[32:35]
	v_mfma_f32_16x16x32_bf16 v[24:27], v[156:159], v[188:191], v[24:27]
	v_mfma_f32_16x16x32_bf16 v[16:19], v[148:151], v[196:199], v[16:19]
	v_mfma_f32_16x16x32_bf16 v[8:11], v[156:159], v[196:199], v[8:11]
	v_mfma_f32_16x16x32_bf16 v[60:63], v[152:155], v[176:179], v[60:63]
	v_mfma_f32_16x16x32_bf16 v[56:59], v[160:163], v[176:179], v[56:59]
	v_mfma_f32_16x16x32_bf16 v[48:51], v[152:155], v[184:187], v[48:51]
	v_mfma_f32_16x16x32_bf16 v[40:43], v[160:163], v[184:187], v[40:43]
	v_mfma_f32_16x16x32_bf16 v[32:35], v[152:155], v[192:195], v[32:35]
	v_mfma_f32_16x16x32_bf16 v[24:27], v[160:163], v[192:195], v[24:27]
	v_mfma_f32_16x16x32_bf16 v[16:19], v[152:155], v[200:203], v[16:19]
	v_mfma_f32_16x16x32_bf16 v[8:11], v[160:163], v[200:203], v[8:11]

	s_barrier
	s_add_u32 s24, s24, 0x80080
	s_addc_u32 s25, s25, 0
	s_add_i32 s26, s26, s31
	s_mov_b32 m0, s26
	s_nop 0

	global_load_lds_dwordx4 v172, s[24:25]
	s_add_i32 m0, s26, 0x2000
	s_nop 0

	global_load_lds_dwordx4 v174, s[24:25]
	s_waitcnt vmcnt(6)
	s_barrier

	v_mfma_f32_16x16x32_bf16 v[52:55], v[204:207], v[164:167], v[52:55]
	v_mfma_f32_16x16x32_bf16 v[44:47], v[222:225], v[164:167], v[44:47]
	v_mfma_f32_16x16x32_bf16 v[36:39], v[204:207], v[180:183], v[36:39]
	v_mfma_f32_16x16x32_bf16 v[28:31], v[222:225], v[180:183], v[28:31]
	v_mfma_f32_16x16x32_bf16 v[20:23], v[204:207], v[188:191], v[20:23]
	v_mfma_f32_16x16x32_bf16 v[12:15], v[222:225], v[188:191], v[12:15]
	v_mfma_f32_16x16x32_bf16 v[4:7], v[204:207], v[196:199], v[4:7]
	v_mfma_f32_16x16x32_bf16 v[0:3], v[222:225], v[196:199], v[0:3]
	v_mfma_f32_16x16x32_bf16 v[52:55], v[218:221], v[176:179], v[52:55]
	v_mfma_f32_16x16x32_bf16 v[44:47], v[226:229], v[176:179], v[44:47]
	v_mfma_f32_16x16x32_bf16 v[36:39], v[218:221], v[184:187], v[36:39]
	v_mfma_f32_16x16x32_bf16 v[28:31], v[226:229], v[184:187], v[28:31]
	v_mfma_f32_16x16x32_bf16 v[20:23], v[218:221], v[192:195], v[20:23]
	v_mfma_f32_16x16x32_bf16 v[12:15], v[226:229], v[192:195], v[12:15]
	v_mfma_f32_16x16x32_bf16 v[4:7], v[218:221], v[200:203], v[4:7]
	v_mfma_f32_16x16x32_bf16 v[0:3], v[226:229], v[200:203], v[0:3]

	s_add_i32 s53, s53, 2
	s_add_u32 s22, s22, 0x100
	s_addc_u32 s23, s23, 0
	s_add_u32 s51, s51, 0x100
	s_addc_u32 s52, s52, 0
	s_cmp_gt_u32 s53, 29
	s_barrier
	s_cbranch_scc0 .LBB0_1167
	s_lshl_b32 s13, s20, 8
	v_mov_b32_e32 v138, v210
	v_mov_b32_e32 v142, v169
	s_add_i32 s13, s13, s39
	s_lshl_b32 s15, s48, 7
	v_add_u32_e32 v136, s13, v142
	v_ashrrev_i32_e32 v137, 31, v136
	v_lshl_add_u64 v[140:141], v[136:137], 2, s[2:3]
	global_load_dword v154, v[140:141], off
	global_load_dword v152, v[140:141], off offset:64
	v_lshl_add_u32 v138, v138, 4, v142
	v_and_b32_e32 v142, 3, v142
	v_ashrrev_i32_e32 v144, 2, v138
	v_and_b32_e32 v138, -4, v138
	v_lshl_or_b32 v146, v142, 2, s15
	v_add_u32_e32 v151, s13, v144
	v_lshl_add_u32 v149, v142, 6, v138
	v_or_b32_e32 v156, s40, v146
	global_load_dword v150, v[140:141], off offset:128
	global_load_dword v148, v[140:141], off offset:192
	global_load_dword v146, v[140:141], off offset:512
	global_load_dword v144, v[140:141], off offset:576
	global_load_dword v142, v[140:141], off offset:640
	global_load_dword v138, v[140:141], off offset:704
	v_mov_b64_e32 v[136:137], s[0:1]
	v_ashrrev_i32_e32 v157, 31, v156
	v_mad_i64_i32 v[158:159], s[22:23], v151, s47, v[136:137]
	v_lshlrev_b64 v[140:141], 1, v[156:157]
	v_lshl_add_u64 v[156:157], v[158:159], 0, v[140:141]
	v_add_u32_e32 v153, 16, v151
	s_and_b64 vcc, exec, s[4:5]
	s_mov_b32 s48, s12
	s_mov_b32 s20, s14
	s_mov_b64 s[24:25], s[18:19]
	s_waitcnt vmcnt(0)
	v_pk_mul_f32 v[126:127], v[126:127], v[154:155] op_sel_hi:[1,0]
	v_pk_mul_f32 v[124:125], v[124:125], v[154:155] op_sel_hi:[1,0]
	v_pk_mul_f32 v[114:115], v[114:115], v[154:155] op_sel_hi:[1,0]
	v_pk_mul_f32 v[112:113], v[112:113], v[154:155] op_sel_hi:[1,0]
	v_pk_mul_f32 v[122:123], v[122:123], v[154:155] op_sel_hi:[1,0]
	v_pk_mul_f32 v[120:121], v[120:121], v[154:155] op_sel_hi:[1,0]
	v_pk_mul_f32 v[110:111], v[110:111], v[154:155] op_sel_hi:[1,0]
	v_pk_mul_f32 v[108:109], v[108:109], v[154:155] op_sel_hi:[1,0]
	v_mul_f32_e32 v154, 0xbfb8aa3b, v124
	v_mul_f32_e32 v155, 0xbfb8aa3b, v125
	v_mul_f32_e32 v158, 0xbfb8aa3b, v126
	v_mul_f32_e32 v159, 0xbfb8aa3b, v127
	v_mul_f32_e32 v160, 0xbfb8aa3b, v120
	v_mul_f32_e32 v161, 0xbfb8aa3b, v121
	v_mul_f32_e32 v162, 0xbfb8aa3b, v122
	v_mul_f32_e32 v163, 0xbfb8aa3b, v123
	v_exp_f32_e32 v154, v154
	v_exp_f32_e32 v155, v155
	v_exp_f32_e32 v158, v158
	v_exp_f32_e32 v159, v159
	v_exp_f32_e32 v160, v160
	v_exp_f32_e32 v161, v161
	v_exp_f32_e32 v162, v162
	v_exp_f32_e32 v163, v163
	v_add_f32_e32 v154, 1.0, v154
	v_add_f32_e32 v155, 1.0, v155
	v_add_f32_e32 v158, 1.0, v158
	v_add_f32_e32 v159, 1.0, v159
	v_add_f32_e32 v160, 1.0, v160
	v_add_f32_e32 v161, 1.0, v161
	v_add_f32_e32 v162, 1.0, v162
	v_add_f32_e32 v163, 1.0, v163
	v_rcp_f32_e32 v154, v154
	v_rcp_f32_e32 v155, v155
	v_rcp_f32_e32 v158, v158
	v_rcp_f32_e32 v159, v159
	v_rcp_f32_e32 v160, v160
	v_rcp_f32_e32 v161, v161
	v_rcp_f32_e32 v162, v162
	v_rcp_f32_e32 v163, v163
	v_pk_mul_f32 v[124:125], v[124:125], v[154:155]
	v_pk_mul_f32 v[126:127], v[126:127], v[158:159]
	v_pk_mul_f32 v[120:121], v[120:121], v[160:161]
	v_pk_mul_f32 v[122:123], v[122:123], v[162:163]
	v_pk_mul_f32 v[112:113], v[112:113], v[124:125]
	v_pk_mul_f32 v[114:115], v[114:115], v[126:127]
	v_pk_mul_f32 v[118:119], v[118:119], v[152:153] op_sel_hi:[1,0]
	v_pk_mul_f32 v[116:117], v[116:117], v[152:153] op_sel_hi:[1,0]
	v_pk_mul_f32 v[108:109], v[108:109], v[120:121]
	v_pk_mul_f32 v[110:111], v[110:111], v[122:123]
	v_cvt_pk_bf16_f32 v112, v112, v113
	v_cvt_pk_bf16_f32 v113, v114, v115
	v_mul_f32_e32 v164, 0xbfb8aa3b, v116
	v_mul_f32_e32 v165, 0xbfb8aa3b, v117
	v_mul_f32_e32 v166, 0xbfb8aa3b, v118
	v_mul_f32_e32 v167, 0xbfb8aa3b, v119
	v_cvt_pk_bf16_f32 v114, v108, v109
	v_cvt_pk_bf16_f32 v111, v110, v111
	ds_bpermute_b32 v108, v149, v112
	ds_bpermute_b32 v109, v149, v113
	v_exp_f32_e32 v164, v164
	v_exp_f32_e32 v165, v165
	v_exp_f32_e32 v166, v166
	v_exp_f32_e32 v167, v167
	ds_bpermute_b32 v110, v149, v114
	ds_bpermute_b32 v111, v149, v111
	v_add_f32_e32 v164, 1.0, v164
	v_add_f32_e32 v113, 1.0, v165
	s_waitcnt lgkmcnt(0)
	global_store_dwordx2 v[156:157], v[108:109], off
	global_store_dwordx2 v[156:157], v[110:111], off offset:32
	v_add_f32_e32 v108, 1.0, v166
	v_add_f32_e32 v109, 1.0, v167
	v_rcp_f32_e32 v112, v164
	v_rcp_f32_e32 v113, v113
	v_rcp_f32_e32 v108, v108
	v_rcp_f32_e32 v109, v109
	v_pk_mul_f32 v[102:103], v[102:103], v[152:153] op_sel_hi:[1,0]
	v_pk_mul_f32 v[100:101], v[100:101], v[152:153] op_sel_hi:[1,0]
	v_pk_mul_f32 v[110:111], v[116:117], v[112:113]
	v_pk_mul_f32 v[108:109], v[118:119], v[108:109]
	v_pk_mul_f32 v[100:101], v[100:101], v[110:111]
	v_pk_mul_f32 v[102:103], v[102:103], v[108:109]
	v_cvt_pk_bf16_f32 v100, v100, v101
	v_cvt_pk_bf16_f32 v101, v102, v103
	v_pk_mul_f32 v[102:103], v[106:107], v[152:153] op_sel_hi:[1,0]
	v_pk_mul_f32 v[104:105], v[104:105], v[152:153] op_sel_hi:[1,0]
	v_mul_f32_e32 v108, 0xbfb8aa3b, v102
	v_mul_f32_e32 v106, 0xbfb8aa3b, v104
	v_mul_f32_e32 v107, 0xbfb8aa3b, v105
	v_mul_f32_e32 v109, 0xbfb8aa3b, v103
	v_exp_f32_e32 v106, v106
	v_exp_f32_e32 v107, v107
	v_exp_f32_e32 v108, v108
	v_exp_f32_e32 v109, v109
	v_add_f32_e32 v106, 1.0, v106
	v_add_f32_e32 v107, 1.0, v107
	v_add_f32_e32 v108, 1.0, v108
	v_add_f32_e32 v109, 1.0, v109
	v_rcp_f32_e32 v106, v106
	v_rcp_f32_e32 v107, v107
	v_rcp_f32_e32 v108, v108
	v_rcp_f32_e32 v109, v109
	v_pk_mul_f32 v[94:95], v[94:95], v[152:153] op_sel_hi:[1,0]
	v_pk_mul_f32 v[92:93], v[92:93], v[152:153] op_sel_hi:[1,0]
	v_pk_mul_f32 v[104:105], v[104:105], v[106:107]
	v_pk_mul_f32 v[102:103], v[102:103], v[108:109]
	v_pk_mul_f32 v[92:93], v[92:93], v[104:105]
	v_pk_mul_f32 v[94:95], v[94:95], v[102:103]
	ds_bpermute_b32 v100, v149, v100
	ds_bpermute_b32 v101, v149, v101
	v_cvt_pk_bf16_f32 v92, v92, v93
	v_cvt_pk_bf16_f32 v93, v94, v95
	ds_bpermute_b32 v92, v149, v92
	ds_bpermute_b32 v93, v149, v93
	v_mad_i64_i32 v[94:95], s[22:23], v153, s47, v[136:137]
	v_lshl_add_u64 v[94:95], v[94:95], 0, v[140:141]
	s_waitcnt lgkmcnt(2)
	global_store_dwordx2 v[94:95], v[100:101], off
	s_waitcnt lgkmcnt(0)
	global_store_dwordx2 v[94:95], v[92:93], off offset:32
	v_pk_mul_f32 v[92:93], v[98:99], v[150:151] op_sel_hi:[1,0]
	v_pk_mul_f32 v[94:95], v[96:97], v[150:151] op_sel_hi:[1,0]
	v_mul_f32_e32 v98, 0xbfb8aa3b, v92
	v_mul_f32_e32 v96, 0xbfb8aa3b, v94
	v_mul_f32_e32 v97, 0xbfb8aa3b, v95
	v_mul_f32_e32 v99, 0xbfb8aa3b, v93
	v_exp_f32_e32 v96, v96
	v_exp_f32_e32 v97, v97
	v_exp_f32_e32 v98, v98
	v_exp_f32_e32 v99, v99
	v_add_f32_e32 v96, 1.0, v96
	v_add_f32_e32 v97, 1.0, v97
	v_add_f32_e32 v98, 1.0, v98
	v_add_f32_e32 v99, 1.0, v99
	v_rcp_f32_e32 v96, v96
	v_rcp_f32_e32 v97, v97
	v_rcp_f32_e32 v98, v98
	v_rcp_f32_e32 v99, v99
	v_pk_mul_f32 v[86:87], v[86:87], v[150:151] op_sel_hi:[1,0]
	v_pk_mul_f32 v[84:85], v[84:85], v[150:151] op_sel_hi:[1,0]
	v_pk_mul_f32 v[94:95], v[94:95], v[96:97]
	v_pk_mul_f32 v[92:93], v[92:93], v[98:99]
	v_pk_mul_f32 v[84:85], v[84:85], v[94:95]
	v_pk_mul_f32 v[86:87], v[86:87], v[92:93]
	v_cvt_pk_bf16_f32 v84, v84, v85
	v_cvt_pk_bf16_f32 v85, v86, v87
	v_pk_mul_f32 v[86:87], v[90:91], v[150:151] op_sel_hi:[1,0]
	v_pk_mul_f32 v[88:89], v[88:89], v[150:151] op_sel_hi:[1,0]
	v_mul_f32_e32 v92, 0xbfb8aa3b, v86
	v_mul_f32_e32 v90, 0xbfb8aa3b, v88
	v_mul_f32_e32 v91, 0xbfb8aa3b, v89
	v_mul_f32_e32 v93, 0xbfb8aa3b, v87
	v_exp_f32_e32 v90, v90
	v_exp_f32_e32 v91, v91
	v_exp_f32_e32 v92, v92
	v_exp_f32_e32 v93, v93
	v_add_f32_e32 v90, 1.0, v90
	v_add_f32_e32 v91, 1.0, v91
	v_add_f32_e32 v92, 1.0, v92
	v_add_f32_e32 v93, 1.0, v93
	v_rcp_f32_e32 v90, v90
	v_rcp_f32_e32 v91, v91
	v_rcp_f32_e32 v92, v92
	v_rcp_f32_e32 v93, v93
	v_pk_mul_f32 v[78:79], v[78:79], v[150:151] op_sel_hi:[1,0]
	v_pk_mul_f32 v[76:77], v[76:77], v[150:151] op_sel_hi:[1,0]
	v_pk_mul_f32 v[88:89], v[88:89], v[90:91]
	v_pk_mul_f32 v[86:87], v[86:87], v[92:93]
	v_pk_mul_f32 v[76:77], v[76:77], v[88:89]
	v_pk_mul_f32 v[78:79], v[78:79], v[86:87]
	ds_bpermute_b32 v84, v149, v84
	ds_bpermute_b32 v85, v149, v85
	v_cvt_pk_bf16_f32 v76, v76, v77
	v_cvt_pk_bf16_f32 v77, v78, v79
	ds_bpermute_b32 v76, v149, v76
	ds_bpermute_b32 v77, v149, v77
	v_add_u32_e32 v100, 32, v151
	v_mad_i64_i32 v[78:79], s[22:23], v100, s47, v[136:137]
	v_lshl_add_u64 v[78:79], v[78:79], 0, v[140:141]
	s_waitcnt lgkmcnt(2)
	global_store_dwordx2 v[78:79], v[84:85], off
	s_waitcnt lgkmcnt(0)
	global_store_dwordx2 v[78:79], v[76:77], off offset:32
	v_pk_mul_f32 v[76:77], v[82:83], v[148:149] op_sel_hi:[1,0]
	v_pk_mul_f32 v[78:79], v[80:81], v[148:149] op_sel_hi:[1,0]
	v_mul_f32_e32 v82, 0xbfb8aa3b, v76
	v_mul_f32_e32 v80, 0xbfb8aa3b, v78
	v_mul_f32_e32 v81, 0xbfb8aa3b, v79
	v_mul_f32_e32 v83, 0xbfb8aa3b, v77
	v_exp_f32_e32 v80, v80
	v_exp_f32_e32 v81, v81
	v_exp_f32_e32 v82, v82
	v_exp_f32_e32 v83, v83
	v_add_f32_e32 v80, 1.0, v80
	v_add_f32_e32 v81, 1.0, v81
	v_add_f32_e32 v82, 1.0, v82
	v_add_f32_e32 v83, 1.0, v83
	v_rcp_f32_e32 v80, v80
	v_rcp_f32_e32 v81, v81
	v_rcp_f32_e32 v82, v82
	v_rcp_f32_e32 v83, v83
	v_pk_mul_f32 v[70:71], v[70:71], v[148:149] op_sel_hi:[1,0]
	v_pk_mul_f32 v[68:69], v[68:69], v[148:149] op_sel_hi:[1,0]
	v_pk_mul_f32 v[78:79], v[78:79], v[80:81]
	v_pk_mul_f32 v[76:77], v[76:77], v[82:83]
	v_pk_mul_f32 v[68:69], v[68:69], v[78:79]
	v_pk_mul_f32 v[70:71], v[70:71], v[76:77]
	v_cvt_pk_bf16_f32 v68, v68, v69
	v_cvt_pk_bf16_f32 v69, v70, v71
	v_pk_mul_f32 v[70:71], v[74:75], v[148:149] op_sel_hi:[1,0]
	v_pk_mul_f32 v[72:73], v[72:73], v[148:149] op_sel_hi:[1,0]
	v_mul_f32_e32 v76, 0xbfb8aa3b, v70
	v_mul_f32_e32 v74, 0xbfb8aa3b, v72
	v_mul_f32_e32 v75, 0xbfb8aa3b, v73
	v_mul_f32_e32 v77, 0xbfb8aa3b, v71
	v_exp_f32_e32 v74, v74
	v_exp_f32_e32 v75, v75
	v_exp_f32_e32 v76, v76
	v_exp_f32_e32 v77, v77
	v_add_f32_e32 v74, 1.0, v74
	v_add_f32_e32 v75, 1.0, v75
	v_add_f32_e32 v76, 1.0, v76
	v_add_f32_e32 v77, 1.0, v77
	v_rcp_f32_e32 v74, v74
	v_rcp_f32_e32 v75, v75
	v_rcp_f32_e32 v76, v76
	v_rcp_f32_e32 v77, v77
	v_pk_mul_f32 v[66:67], v[66:67], v[148:149] op_sel_hi:[1,0]
	v_pk_mul_f32 v[64:65], v[64:65], v[148:149] op_sel_hi:[1,0]
	v_pk_mul_f32 v[72:73], v[72:73], v[74:75]
	v_pk_mul_f32 v[70:71], v[70:71], v[76:77]
	v_pk_mul_f32 v[64:65], v[64:65], v[72:73]
	v_pk_mul_f32 v[66:67], v[66:67], v[70:71]
	ds_bpermute_b32 v68, v149, v68
	ds_bpermute_b32 v69, v149, v69
	v_cvt_pk_bf16_f32 v64, v64, v65
	v_cvt_pk_bf16_f32 v65, v66, v67
	ds_bpermute_b32 v64, v149, v64
	ds_bpermute_b32 v65, v149, v65
	v_add_u32_e32 v84, 48, v151
	v_mad_i64_i32 v[66:67], s[22:23], v84, s47, v[136:137]
	v_lshl_add_u64 v[66:67], v[66:67], 0, v[140:141]
	v_pk_mul_f32 v[60:61], v[60:61], v[146:147] op_sel_hi:[1,0]
	s_waitcnt lgkmcnt(2)
	global_store_dwordx2 v[66:67], v[68:69], off
	s_waitcnt lgkmcnt(0)
	global_store_dwordx2 v[66:67], v[64:65], off offset:32
	v_pk_mul_f32 v[62:63], v[62:63], v[146:147] op_sel_hi:[1,0]
	v_mul_f32_e32 v64, 0xbfb8aa3b, v60
	v_mul_f32_e32 v65, 0xbfb8aa3b, v61
	v_exp_f32_e32 v64, v64
	v_exp_f32_e32 v65, v65
	v_mul_f32_e32 v66, 0xbfb8aa3b, v62
	v_mul_f32_e32 v67, 0xbfb8aa3b, v63
	v_exp_f32_e32 v66, v66
	v_exp_f32_e32 v67, v67
	v_add_f32_e32 v64, 1.0, v64
	v_add_f32_e32 v65, 1.0, v65
	v_rcp_f32_e32 v64, v64
	v_rcp_f32_e32 v65, v65
	v_add_f32_e32 v66, 1.0, v66
	v_add_f32_e32 v67, 1.0, v67
	v_rcp_f32_e32 v66, v66
	v_rcp_f32_e32 v67, v67
	v_pk_mul_f32 v[52:53], v[52:53], v[146:147] op_sel_hi:[1,0]
	v_pk_mul_f32 v[60:61], v[60:61], v[64:65]
	v_pk_mul_f32 v[54:55], v[54:55], v[146:147] op_sel_hi:[1,0]
	v_pk_mul_f32 v[52:53], v[52:53], v[60:61]
	v_pk_mul_f32 v[60:61], v[62:63], v[66:67]
	v_cvt_pk_bf16_f32 v52, v52, v53
	v_pk_mul_f32 v[54:55], v[54:55], v[60:61]
	v_pk_mul_f32 v[56:57], v[56:57], v[146:147] op_sel_hi:[1,0]
	v_cvt_pk_bf16_f32 v53, v54, v55
	v_pk_mul_f32 v[54:55], v[58:59], v[146:147] op_sel_hi:[1,0]
	v_mul_f32_e32 v58, 0xbfb8aa3b, v56
	v_mul_f32_e32 v59, 0xbfb8aa3b, v57
	v_mul_f32_e32 v60, 0xbfb8aa3b, v54
	v_mul_f32_e32 v61, 0xbfb8aa3b, v55
	v_exp_f32_e32 v58, v58
	v_exp_f32_e32 v59, v59
	v_exp_f32_e32 v60, v60
	v_exp_f32_e32 v61, v61
	v_add_f32_e32 v58, 1.0, v58
	v_add_f32_e32 v59, 1.0, v59
	v_add_f32_e32 v60, 1.0, v60
	v_add_f32_e32 v61, 1.0, v61
	v_rcp_f32_e32 v58, v58
	v_rcp_f32_e32 v59, v59
	v_rcp_f32_e32 v60, v60
	v_rcp_f32_e32 v61, v61
	v_pk_mul_f32 v[46:47], v[46:47], v[146:147] op_sel_hi:[1,0]
	v_pk_mul_f32 v[44:45], v[44:45], v[146:147] op_sel_hi:[1,0]
	v_pk_mul_f32 v[56:57], v[56:57], v[58:59]
	v_pk_mul_f32 v[54:55], v[54:55], v[60:61]
	v_pk_mul_f32 v[44:45], v[44:45], v[56:57]
	v_pk_mul_f32 v[46:47], v[46:47], v[54:55]
	ds_bpermute_b32 v52, v149, v52
	ds_bpermute_b32 v53, v149, v53
	v_cvt_pk_bf16_f32 v44, v44, v45
	v_cvt_pk_bf16_f32 v45, v46, v47
	ds_bpermute_b32 v44, v149, v44
	ds_bpermute_b32 v45, v149, v45
	v_add_u32_e32 v68, 0x80, v151
	v_mad_i64_i32 v[46:47], s[22:23], v68, s47, v[136:137]
	v_lshl_add_u64 v[46:47], v[46:47], 0, v[140:141]
	s_waitcnt lgkmcnt(2)
	global_store_dwordx2 v[46:47], v[52:53], off
	s_waitcnt lgkmcnt(0)
	global_store_dwordx2 v[46:47], v[44:45], off offset:32
	v_pk_mul_f32 v[44:45], v[50:51], v[144:145] op_sel_hi:[1,0]
	v_pk_mul_f32 v[46:47], v[48:49], v[144:145] op_sel_hi:[1,0]
	v_mul_f32_e32 v50, 0xbfb8aa3b, v44
	v_mul_f32_e32 v48, 0xbfb8aa3b, v46
	v_mul_f32_e32 v49, 0xbfb8aa3b, v47
	v_mul_f32_e32 v51, 0xbfb8aa3b, v45
	v_exp_f32_e32 v48, v48
	v_exp_f32_e32 v49, v49
	v_exp_f32_e32 v50, v50
	v_exp_f32_e32 v51, v51
	v_add_f32_e32 v48, 1.0, v48
	v_add_f32_e32 v49, 1.0, v49
	v_add_f32_e32 v50, 1.0, v50
	v_add_f32_e32 v51, 1.0, v51
	v_rcp_f32_e32 v48, v48
	v_rcp_f32_e32 v49, v49
	v_rcp_f32_e32 v50, v50
	v_rcp_f32_e32 v51, v51
	v_pk_mul_f32 v[38:39], v[38:39], v[144:145] op_sel_hi:[1,0]
	v_pk_mul_f32 v[36:37], v[36:37], v[144:145] op_sel_hi:[1,0]
	v_pk_mul_f32 v[46:47], v[46:47], v[48:49]
	v_pk_mul_f32 v[44:45], v[44:45], v[50:51]
	v_pk_mul_f32 v[36:37], v[36:37], v[46:47]
	v_pk_mul_f32 v[38:39], v[38:39], v[44:45]
	v_cvt_pk_bf16_f32 v36, v36, v37
	v_cvt_pk_bf16_f32 v37, v38, v39
	v_pk_mul_f32 v[38:39], v[42:43], v[144:145] op_sel_hi:[1,0]
	v_pk_mul_f32 v[40:41], v[40:41], v[144:145] op_sel_hi:[1,0]
	v_mul_f32_e32 v44, 0xbfb8aa3b, v38
	v_mul_f32_e32 v42, 0xbfb8aa3b, v40
	v_mul_f32_e32 v43, 0xbfb8aa3b, v41
	v_mul_f32_e32 v45, 0xbfb8aa3b, v39
	v_exp_f32_e32 v42, v42
	v_exp_f32_e32 v43, v43
	v_exp_f32_e32 v44, v44
	v_exp_f32_e32 v45, v45
	v_add_f32_e32 v42, 1.0, v42
	v_add_f32_e32 v43, 1.0, v43
	v_add_f32_e32 v44, 1.0, v44
	v_add_f32_e32 v45, 1.0, v45
	v_rcp_f32_e32 v42, v42
	v_rcp_f32_e32 v43, v43
	v_rcp_f32_e32 v44, v44
	v_rcp_f32_e32 v45, v45
	v_pk_mul_f32 v[30:31], v[30:31], v[144:145] op_sel_hi:[1,0]
	v_pk_mul_f32 v[28:29], v[28:29], v[144:145] op_sel_hi:[1,0]
	v_pk_mul_f32 v[40:41], v[40:41], v[42:43]
	v_pk_mul_f32 v[38:39], v[38:39], v[44:45]
	v_pk_mul_f32 v[28:29], v[28:29], v[40:41]
	v_pk_mul_f32 v[30:31], v[30:31], v[38:39]
	ds_bpermute_b32 v36, v149, v36
	ds_bpermute_b32 v37, v149, v37
	v_cvt_pk_bf16_f32 v28, v28, v29
	v_cvt_pk_bf16_f32 v29, v30, v31
	ds_bpermute_b32 v28, v149, v28
	ds_bpermute_b32 v29, v149, v29
	v_add_u32_e32 v52, 0x90, v151
	v_mad_i64_i32 v[30:31], s[22:23], v52, s47, v[136:137]
	v_lshl_add_u64 v[30:31], v[30:31], 0, v[140:141]
	s_waitcnt lgkmcnt(2)
	global_store_dwordx2 v[30:31], v[36:37], off
	s_waitcnt lgkmcnt(0)
	global_store_dwordx2 v[30:31], v[28:29], off offset:32
	v_pk_mul_f32 v[28:29], v[34:35], v[142:143] op_sel_hi:[1,0]
	v_pk_mul_f32 v[30:31], v[32:33], v[142:143] op_sel_hi:[1,0]
	v_mul_f32_e32 v34, 0xbfb8aa3b, v28
	v_mul_f32_e32 v32, 0xbfb8aa3b, v30
	v_mul_f32_e32 v33, 0xbfb8aa3b, v31
	v_mul_f32_e32 v35, 0xbfb8aa3b, v29
	v_exp_f32_e32 v32, v32
	v_exp_f32_e32 v33, v33
	v_exp_f32_e32 v34, v34
	v_exp_f32_e32 v35, v35
	v_add_f32_e32 v32, 1.0, v32
	v_add_f32_e32 v33, 1.0, v33
	v_add_f32_e32 v34, 1.0, v34
	v_add_f32_e32 v35, 1.0, v35
	v_rcp_f32_e32 v32, v32
	v_rcp_f32_e32 v33, v33
	v_rcp_f32_e32 v34, v34
	v_rcp_f32_e32 v35, v35
	v_pk_mul_f32 v[22:23], v[22:23], v[142:143] op_sel_hi:[1,0]
	v_pk_mul_f32 v[20:21], v[20:21], v[142:143] op_sel_hi:[1,0]
	v_pk_mul_f32 v[30:31], v[30:31], v[32:33]
	v_pk_mul_f32 v[28:29], v[28:29], v[34:35]
	v_pk_mul_f32 v[20:21], v[20:21], v[30:31]
	v_pk_mul_f32 v[22:23], v[22:23], v[28:29]
	v_cvt_pk_bf16_f32 v20, v20, v21
	v_cvt_pk_bf16_f32 v21, v22, v23
	v_pk_mul_f32 v[22:23], v[26:27], v[142:143] op_sel_hi:[1,0]
	v_pk_mul_f32 v[24:25], v[24:25], v[142:143] op_sel_hi:[1,0]
	v_mul_f32_e32 v28, 0xbfb8aa3b, v22
	v_mul_f32_e32 v26, 0xbfb8aa3b, v24
	v_mul_f32_e32 v27, 0xbfb8aa3b, v25
	v_mul_f32_e32 v29, 0xbfb8aa3b, v23
	v_exp_f32_e32 v26, v26
	v_exp_f32_e32 v27, v27
	v_exp_f32_e32 v28, v28
	v_exp_f32_e32 v29, v29
	v_add_f32_e32 v26, 1.0, v26
	v_add_f32_e32 v27, 1.0, v27
	v_add_f32_e32 v28, 1.0, v28
	v_add_f32_e32 v29, 1.0, v29
	v_rcp_f32_e32 v26, v26
	v_rcp_f32_e32 v27, v27
	v_rcp_f32_e32 v28, v28
	v_rcp_f32_e32 v29, v29
	v_pk_mul_f32 v[14:15], v[14:15], v[142:143] op_sel_hi:[1,0]
	v_pk_mul_f32 v[12:13], v[12:13], v[142:143] op_sel_hi:[1,0]
	v_pk_mul_f32 v[24:25], v[24:25], v[26:27]
	v_pk_mul_f32 v[22:23], v[22:23], v[28:29]
	v_pk_mul_f32 v[12:13], v[12:13], v[24:25]
	v_pk_mul_f32 v[14:15], v[14:15], v[22:23]
	ds_bpermute_b32 v20, v149, v20
	ds_bpermute_b32 v21, v149, v21
	v_cvt_pk_bf16_f32 v12, v12, v13
	v_cvt_pk_bf16_f32 v13, v14, v15
	ds_bpermute_b32 v12, v149, v12
	ds_bpermute_b32 v13, v149, v13
	v_add_u32_e32 v36, 0xa0, v151
	v_mad_i64_i32 v[14:15], s[22:23], v36, s47, v[136:137]
	v_lshl_add_u64 v[14:15], v[14:15], 0, v[140:141]
	s_waitcnt lgkmcnt(2)
	global_store_dwordx2 v[14:15], v[20:21], off
	s_waitcnt lgkmcnt(0)
	global_store_dwordx2 v[14:15], v[12:13], off offset:32
	v_pk_mul_f32 v[12:13], v[18:19], v[138:139] op_sel_hi:[1,0]
	v_pk_mul_f32 v[14:15], v[16:17], v[138:139] op_sel_hi:[1,0]
	v_mul_f32_e32 v18, 0xbfb8aa3b, v12
	v_mul_f32_e32 v16, 0xbfb8aa3b, v14
	v_mul_f32_e32 v17, 0xbfb8aa3b, v15
	v_mul_f32_e32 v19, 0xbfb8aa3b, v13
	v_exp_f32_e32 v16, v16
	v_exp_f32_e32 v17, v17
	v_exp_f32_e32 v18, v18
	v_exp_f32_e32 v19, v19
	v_add_f32_e32 v16, 1.0, v16
	v_add_f32_e32 v17, 1.0, v17
	v_add_f32_e32 v18, 1.0, v18
	v_add_f32_e32 v19, 1.0, v19
	v_rcp_f32_e32 v16, v16
	v_rcp_f32_e32 v17, v17
	v_rcp_f32_e32 v18, v18
	v_rcp_f32_e32 v19, v19
	v_pk_mul_f32 v[6:7], v[6:7], v[138:139] op_sel_hi:[1,0]
	v_pk_mul_f32 v[4:5], v[4:5], v[138:139] op_sel_hi:[1,0]
	v_pk_mul_f32 v[14:15], v[14:15], v[16:17]
	v_pk_mul_f32 v[12:13], v[12:13], v[18:19]
	v_pk_mul_f32 v[4:5], v[4:5], v[14:15]
	v_pk_mul_f32 v[6:7], v[6:7], v[12:13]
	v_cvt_pk_bf16_f32 v4, v4, v5
	v_cvt_pk_bf16_f32 v5, v6, v7
	v_pk_mul_f32 v[6:7], v[10:11], v[138:139] op_sel_hi:[1,0]
	v_pk_mul_f32 v[8:9], v[8:9], v[138:139] op_sel_hi:[1,0]
	v_mul_f32_e32 v12, 0xbfb8aa3b, v6
	v_mul_f32_e32 v10, 0xbfb8aa3b, v8
	v_mul_f32_e32 v11, 0xbfb8aa3b, v9
	v_mul_f32_e32 v13, 0xbfb8aa3b, v7
	v_exp_f32_e32 v10, v10
	v_exp_f32_e32 v11, v11
	v_exp_f32_e32 v12, v12
	v_exp_f32_e32 v13, v13
	v_add_f32_e32 v10, 1.0, v10
	v_add_f32_e32 v11, 1.0, v11
	v_add_f32_e32 v12, 1.0, v12
	v_add_f32_e32 v13, 1.0, v13
	v_rcp_f32_e32 v10, v10
	v_rcp_f32_e32 v11, v11
	v_rcp_f32_e32 v12, v12
	v_rcp_f32_e32 v13, v13
	v_pk_mul_f32 v[2:3], v[2:3], v[138:139] op_sel_hi:[1,0]
	v_pk_mul_f32 v[0:1], v[0:1], v[138:139] op_sel_hi:[1,0]
	v_pk_mul_f32 v[8:9], v[8:9], v[10:11]
	v_pk_mul_f32 v[6:7], v[6:7], v[12:13]
	v_pk_mul_f32 v[0:1], v[0:1], v[8:9]
	v_pk_mul_f32 v[2:3], v[2:3], v[6:7]
	ds_bpermute_b32 v4, v149, v4
	ds_bpermute_b32 v5, v149, v5
	v_cvt_pk_bf16_f32 v0, v0, v1
	v_cvt_pk_bf16_f32 v1, v2, v3
	ds_bpermute_b32 v0, v149, v0
	ds_bpermute_b32 v1, v149, v1
	v_add_u32_e32 v20, 0xb0, v151
	v_mad_i64_i32 v[2:3], s[22:23], v20, s47, v[136:137]
	v_lshl_add_u64 v[2:3], v[2:3], 0, v[140:141]
	s_mov_b64 s[22:23], s[16:17]
	s_waitcnt lgkmcnt(2)
	global_store_dwordx2 v[2:3], v[4:5], off
	s_waitcnt lgkmcnt(0)
	global_store_dwordx2 v[2:3], v[0:1], off offset:32
	s_cbranch_vccz .LBB0_1164
	s_waitcnt vmcnt(0)
	s_cmpk_gt_u32 s28, 0xff
	s_cbranch_scc1 .LBB0_1171
	s_barrier

.LBB0_1258:
	ds_read_b128 v[128:131], v159
	ds_read_b128 v[132:135], v159 offset:1024
	ds_read_b128 v[136:139], v159 offset:2048
	ds_read_b128 v[150:153], v159 offset:3072
	s_add_i32 s54, s18, 2
	s_add_u32 s19, s16, 0xffea0080
	s_addc_u32 s20, s17, -1
	s_cmp_eq_u32 s13, s18
	s_cselect_b32 s18, s4, s52
	s_cselect_b32 s21, s15, s20
	s_cselect_b32 s20, s14, s19
	s_cselect_b32 s19, s5, s53
	v_lshl_add_u64 v[166:167], s[16:17], 0, v[146:147]
	s_add_i32 m0, s26, 0xc000
	ds_read_b128 v[154:157], v160
	ds_read_b128 v[162:165], v160 offset:1024
	ds_read_b128 v[172:175], v160 offset:2048
	ds_read_b128 v[176:179], v160 offset:3072
	ds_read_b128 v[180:183], v160 offset:4096
	ds_read_b128 v[184:187], v160 offset:5120
	ds_read_b128 v[188:191], v160 offset:6144
	ds_read_b128 v[192:195], v160 offset:7168
	global_load_lds_dwordx4 v[166:167], off
	s_add_i32 m0, s26, 0xe000
	s_nop 0

	global_load_lds_dwordx4 v148, s[16:17]
	s_waitcnt lgkmcnt(8)
	s_barrier
	s_waitcnt lgkmcnt(0)


	v_mfma_f32_16x16x32_bf16 v[124:127], v[128:131], v[154:157], v[124:127]
	v_mfma_f32_16x16x32_bf16 v[120:123], v[136:139], v[154:157], v[120:123]
	v_mfma_f32_16x16x32_bf16 v[116:119], v[128:131], v[172:175], v[116:119]
	v_mfma_f32_16x16x32_bf16 v[104:107], v[136:139], v[172:175], v[104:107]
	v_mfma_f32_16x16x32_bf16 v[96:99], v[128:131], v[180:183], v[96:99]
	v_mfma_f32_16x16x32_bf16 v[88:91], v[136:139], v[180:183], v[88:91]
	v_mfma_f32_16x16x32_bf16 v[80:83], v[128:131], v[188:191], v[80:83]
	v_mfma_f32_16x16x32_bf16 v[72:75], v[136:139], v[188:191], v[72:75]
	v_mfma_f32_16x16x32_bf16 v[124:127], v[132:135], v[162:165], v[124:127]
	v_mfma_f32_16x16x32_bf16 v[120:123], v[150:153], v[162:165], v[120:123]
	v_mfma_f32_16x16x32_bf16 v[116:119], v[132:135], v[176:179], v[116:119]
	v_mfma_f32_16x16x32_bf16 v[104:107], v[150:153], v[176:179], v[104:107]
	v_mfma_f32_16x16x32_bf16 v[96:99], v[132:135], v[184:187], v[96:99]
	v_mfma_f32_16x16x32_bf16 v[88:91], v[150:153], v[184:187], v[88:91]
	v_mfma_f32_16x16x32_bf16 v[80:83], v[132:135], v[192:195], v[80:83]
	v_mfma_f32_16x16x32_bf16 v[72:75], v[150:153], v[192:195], v[72:75]

	s_barrier
	s_add_i32 s55, s35, s25
	v_lshl_add_u64 v[166:167], s[18:19], 0, v[140:141]
	s_mov_b32 m0, s55
	ds_read_b128 v[196:199], v161
	ds_read_b128 v[200:203], v161 offset:1024
	ds_read_b128 v[204:207], v161 offset:2048
	ds_read_b128 v[212:215], v161 offset:3072
	global_load_lds_dwordx4 v[166:167], off
	s_add_i32 m0, s55, 0x2000
	v_lshl_add_u64 v[208:209], s[18:19], 0, v[142:143]

	global_load_lds_dwordx4 v[208:209], off
	s_barrier
	s_waitcnt lgkmcnt(0)


	v_mfma_f32_16x16x32_bf16 v[112:115], v[196:199], v[154:157], v[112:115]
	v_mfma_f32_16x16x32_bf16 v[108:111], v[204:207], v[154:157], v[108:111]
	v_mfma_f32_16x16x32_bf16 v[100:103], v[196:199], v[172:175], v[100:103]
	v_mfma_f32_16x16x32_bf16 v[92:95], v[204:207], v[172:175], v[92:95]
	v_mfma_f32_16x16x32_bf16 v[84:87], v[196:199], v[180:183], v[84:87]
	v_mfma_f32_16x16x32_bf16 v[76:79], v[204:207], v[180:183], v[76:79]
	v_mfma_f32_16x16x32_bf16 v[68:71], v[196:199], v[188:191], v[68:71]
	v_mfma_f32_16x16x32_bf16 v[64:67], v[204:207], v[188:191], v[64:67]
	v_mfma_f32_16x16x32_bf16 v[112:115], v[200:203], v[162:165], v[112:115]
	v_mfma_f32_16x16x32_bf16 v[108:111], v[212:215], v[162:165], v[108:111]
	v_mfma_f32_16x16x32_bf16 v[100:103], v[200:203], v[176:179], v[100:103]
	v_mfma_f32_16x16x32_bf16 v[92:95], v[212:215], v[176:179], v[92:95]
	v_mfma_f32_16x16x32_bf16 v[84:87], v[200:203], v[184:187], v[84:87]
	v_mfma_f32_16x16x32_bf16 v[76:79], v[212:215], v[184:187], v[76:79]
	v_mfma_f32_16x16x32_bf16 v[68:71], v[200:203], v[192:195], v[68:71]
	v_mfma_f32_16x16x32_bf16 v[64:67], v[212:215], v[192:195], v[64:67]

	s_mov_b32 m0, s26
	v_lshl_add_u64 v[216:217], s[20:21], 0, v[140:141]
	s_barrier
	ds_read_b128 v[154:157], v160 offset:16384
	ds_read_b128 v[162:165], v160 offset:17408
	ds_read_b128 v[172:175], v160 offset:18432
	ds_read_b128 v[176:179], v160 offset:19456
	ds_read_b128 v[180:183], v160 offset:20480
	ds_read_b128 v[184:187], v160 offset:21504
	ds_read_b128 v[188:191], v160 offset:22528
	ds_read_b128 v[192:195], v160 offset:23552
	global_load_lds_dwordx4 v[216:217], off
	s_mov_b32 m0, s27
	v_lshl_add_u64 v[218:219], s[20:21], 0, v[142:143]

	global_load_lds_dwordx4 v[218:219], off
	s_barrier
	s_waitcnt lgkmcnt(0)


	v_mfma_f32_16x16x32_bf16 v[60:63], v[128:131], v[154:157], v[60:63]
	v_mfma_f32_16x16x32_bf16 v[56:59], v[136:139], v[154:157], v[56:59]
	v_mfma_f32_16x16x32_bf16 v[52:55], v[128:131], v[172:175], v[52:55]
	v_mfma_f32_16x16x32_bf16 v[40:43], v[136:139], v[172:175], v[40:43]
	v_mfma_f32_16x16x32_bf16 v[36:39], v[128:131], v[180:183], v[36:39]
	v_mfma_f32_16x16x32_bf16 v[24:27], v[136:139], v[180:183], v[24:27]
	v_mfma_f32_16x16x32_bf16 v[20:23], v[128:131], v[188:191], v[20:23]
	v_mfma_f32_16x16x32_bf16 v[8:11], v[136:139], v[188:191], v[8:11]
	v_mfma_f32_16x16x32_bf16 v[60:63], v[132:135], v[162:165], v[60:63]
	v_mfma_f32_16x16x32_bf16 v[56:59], v[150:153], v[162:165], v[56:59]
	v_mfma_f32_16x16x32_bf16 v[52:55], v[132:135], v[176:179], v[52:55]
	v_mfma_f32_16x16x32_bf16 v[40:43], v[150:153], v[176:179], v[40:43]
	v_mfma_f32_16x16x32_bf16 v[36:39], v[132:135], v[184:187], v[36:39]
	v_mfma_f32_16x16x32_bf16 v[24:27], v[150:153], v[184:187], v[24:27]
	v_mfma_f32_16x16x32_bf16 v[20:23], v[132:135], v[192:195], v[20:23]
	v_mfma_f32_16x16x32_bf16 v[8:11], v[150:153], v[192:195], v[8:11]

	s_barrier
	s_add_u32 s56, s18, 0x160000
	s_addc_u32 s57, s19, 0
	s_add_i32 s55, s36, s25
	s_mov_b32 m0, s55
	s_nop 0

	global_load_lds_dwordx4 v140, s[56:57]
	s_add_i32 m0, s55, 0x2000
	s_nop 0

	global_load_lds_dwordx4 v142, s[56:57]
	s_waitcnt vmcnt(6)
	s_barrier

	v_mfma_f32_16x16x32_bf16 v[48:51], v[196:199], v[154:157], v[48:51]
	v_mfma_f32_16x16x32_bf16 v[44:47], v[204:207], v[154:157], v[44:47]
	v_mfma_f32_16x16x32_bf16 v[32:35], v[196:199], v[172:175], v[32:35]
	v_mfma_f32_16x16x32_bf16 v[28:31], v[204:207], v[172:175], v[28:31]
	v_mfma_f32_16x16x32_bf16 v[16:19], v[196:199], v[180:183], v[16:19]
	v_mfma_f32_16x16x32_bf16 v[12:15], v[204:207], v[180:183], v[12:15]
	v_mfma_f32_16x16x32_bf16 v[4:7], v[196:199], v[188:191], v[4:7]
	v_mfma_f32_16x16x32_bf16 v[0:3], v[204:207], v[188:191], v[0:3]
	v_mfma_f32_16x16x32_bf16 v[48:51], v[200:203], v[162:165], v[48:51]
	v_mfma_f32_16x16x32_bf16 v[44:47], v[212:215], v[162:165], v[44:47]
	v_mfma_f32_16x16x32_bf16 v[32:35], v[200:203], v[176:179], v[32:35]
	v_mfma_f32_16x16x32_bf16 v[28:31], v[212:215], v[176:179], v[28:31]
	v_mfma_f32_16x16x32_bf16 v[16:19], v[200:203], v[184:187], v[16:19]
	v_mfma_f32_16x16x32_bf16 v[12:15], v[212:215], v[184:187], v[12:15]
	v_mfma_f32_16x16x32_bf16 v[4:7], v[200:203], v[192:195], v[4:7]
	v_mfma_f32_16x16x32_bf16 v[0:3], v[212:215], v[192:195], v[0:3]

	s_add_i32 s55, 0, 0x18000
	v_add_u32_e32 v144, s55, v158
	s_barrier
	ds_read_b128 v[128:131], v144
	ds_read_b128 v[132:135], v144 offset:1024
	ds_read_b128 v[136:139], v144 offset:2048
	ds_read_b128 v[150:153], v144 offset:3072
	s_add_u32 s20, s20, 0x160000
	s_addc_u32 s21, s21, 0
	s_mov_b32 m0, s28
	v_lshl_add_u64 v[196:197], s[20:21], 0, v[140:141]
	ds_read_b128 v[154:157], v160 offset:32768
	ds_read_b128 v[162:165], v160 offset:33792
	ds_read_b128 v[172:175], v160 offset:34816
	ds_read_b128 v[176:179], v160 offset:35840
	ds_read_b128 v[180:183], v160 offset:36864
	ds_read_b128 v[184:187], v160 offset:37888
	ds_read_b128 v[188:191], v160 offset:38912
	ds_read_b128 v[192:195], v160 offset:39936
	global_load_lds_dwordx4 v[196:197], off
	s_mov_b32 m0, s29
	s_nop 0

	global_load_lds_dwordx4 v142, s[20:21]
	s_waitcnt lgkmcnt(8)
	s_barrier
	s_waitcnt lgkmcnt(0)


	v_mfma_f32_16x16x32_bf16 v[124:127], v[128:131], v[154:157], v[124:127]
	v_mfma_f32_16x16x32_bf16 v[120:123], v[136:139], v[154:157], v[120:123]
	v_mfma_f32_16x16x32_bf16 v[116:119], v[128:131], v[172:175], v[116:119]
	v_mfma_f32_16x16x32_bf16 v[104:107], v[136:139], v[172:175], v[104:107]
	v_mfma_f32_16x16x32_bf16 v[96:99], v[128:131], v[180:183], v[96:99]
	v_mfma_f32_16x16x32_bf16 v[88:91], v[136:139], v[180:183], v[88:91]
	v_mfma_f32_16x16x32_bf16 v[80:83], v[128:131], v[188:191], v[80:83]
	v_mfma_f32_16x16x32_bf16 v[72:75], v[136:139], v[188:191], v[72:75]
	v_mfma_f32_16x16x32_bf16 v[124:127], v[132:135], v[162:165], v[124:127]
	v_mfma_f32_16x16x32_bf16 v[120:123], v[150:153], v[162:165], v[120:123]
	v_mfma_f32_16x16x32_bf16 v[116:119], v[132:135], v[176:179], v[116:119]
	v_mfma_f32_16x16x32_bf16 v[104:107], v[150:153], v[176:179], v[104:107]
	v_mfma_f32_16x16x32_bf16 v[96:99], v[132:135], v[184:187], v[96:99]
	v_mfma_f32_16x16x32_bf16 v[88:91], v[150:153], v[184:187], v[88:91]
	v_mfma_f32_16x16x32_bf16 v[80:83], v[132:135], v[192:195], v[80:83]
	v_mfma_f32_16x16x32_bf16 v[72:75], v[150:153], v[192:195], v[72:75]

	s_barrier
	s_add_i32 s20, 0, 0x1c000
	s_add_i32 s21, s55, s25
	v_add_u32_e32 v144, s20, v158
	v_lshl_add_u64 v[166:167], v[166:167], 0, s[6:7]
	s_mov_b32 m0, s21
	ds_read_b128 v[196:199], v144
	ds_read_b128 v[200:203], v144 offset:1024
	ds_read_b128 v[204:207], v144 offset:2048
	ds_read_b128 v[212:215], v144 offset:3072
	global_load_lds_dwordx4 v[166:167], off
	s_add_i32 m0, s21, 0x2000
	v_lshl_add_u64 v[166:167], v[208:209], 0, s[6:7]

	global_load_lds_dwordx4 v[166:167], off
	s_barrier
	s_waitcnt lgkmcnt(0)


	v_mfma_f32_16x16x32_bf16 v[112:115], v[196:199], v[154:157], v[112:115]
	v_mfma_f32_16x16x32_bf16 v[108:111], v[204:207], v[154:157], v[108:111]
	v_mfma_f32_16x16x32_bf16 v[100:103], v[196:199], v[172:175], v[100:103]
	v_mfma_f32_16x16x32_bf16 v[92:95], v[204:207], v[172:175], v[92:95]
	v_mfma_f32_16x16x32_bf16 v[84:87], v[196:199], v[180:183], v[84:87]
	v_mfma_f32_16x16x32_bf16 v[76:79], v[204:207], v[180:183], v[76:79]
	v_mfma_f32_16x16x32_bf16 v[68:71], v[196:199], v[188:191], v[68:71]
	v_mfma_f32_16x16x32_bf16 v[64:67], v[204:207], v[188:191], v[64:67]
	v_mfma_f32_16x16x32_bf16 v[112:115], v[200:203], v[162:165], v[112:115]
	v_mfma_f32_16x16x32_bf16 v[108:111], v[212:215], v[162:165], v[108:111]
	v_mfma_f32_16x16x32_bf16 v[100:103], v[200:203], v[176:179], v[100:103]
	v_mfma_f32_16x16x32_bf16 v[92:95], v[212:215], v[176:179], v[92:95]
	v_mfma_f32_16x16x32_bf16 v[84:87], v[200:203], v[184:187], v[84:87]
	v_mfma_f32_16x16x32_bf16 v[76:79], v[212:215], v[184:187], v[76:79]
	v_mfma_f32_16x16x32_bf16 v[68:71], v[200:203], v[192:195], v[68:71]
	v_mfma_f32_16x16x32_bf16 v[64:67], v[212:215], v[192:195], v[64:67]

	s_mov_b32 m0, s33
	v_lshl_add_u64 v[166:167], v[216:217], 0, s[6:7]
	s_barrier
	ds_read_b128 v[154:157], v160 offset:49152
	ds_read_b128 v[162:165], v160 offset:50176
	ds_read_b128 v[172:175], v160 offset:51200
	ds_read_b128 v[176:179], v160 offset:52224
	ds_read_b128 v[180:183], v160 offset:53248
	ds_read_b128 v[184:187], v160 offset:54272
	ds_read_b128 v[188:191], v160 offset:55296
	ds_read_b128 v[192:195], v160 offset:56320
	global_load_lds_dwordx4 v[166:167], off
	s_mov_b32 m0, s34
	v_lshl_add_u64 v[166:167], v[218:219], 0, s[6:7]

	global_load_lds_dwordx4 v[166:167], off
	s_barrier
	s_waitcnt lgkmcnt(0)


	v_mfma_f32_16x16x32_bf16 v[60:63], v[128:131], v[154:157], v[60:63]
	v_mfma_f32_16x16x32_bf16 v[56:59], v[136:139], v[154:157], v[56:59]
	v_mfma_f32_16x16x32_bf16 v[52:55], v[128:131], v[172:175], v[52:55]
	v_mfma_f32_16x16x32_bf16 v[40:43], v[136:139], v[172:175], v[40:43]
	v_mfma_f32_16x16x32_bf16 v[36:39], v[128:131], v[180:183], v[36:39]
	v_mfma_f32_16x16x32_bf16 v[24:27], v[136:139], v[180:183], v[24:27]
	v_mfma_f32_16x16x32_bf16 v[20:23], v[128:131], v[188:191], v[20:23]
	v_mfma_f32_16x16x32_bf16 v[8:11], v[136:139], v[188:191], v[8:11]
	v_mfma_f32_16x16x32_bf16 v[60:63], v[132:135], v[162:165], v[60:63]
	v_mfma_f32_16x16x32_bf16 v[56:59], v[150:153], v[162:165], v[56:59]
	v_mfma_f32_16x16x32_bf16 v[52:55], v[132:135], v[176:179], v[52:55]
	v_mfma_f32_16x16x32_bf16 v[40:43], v[150:153], v[176:179], v[40:43]
	v_mfma_f32_16x16x32_bf16 v[36:39], v[132:135], v[184:187], v[36:39]
	v_mfma_f32_16x16x32_bf16 v[24:27], v[150:153], v[184:187], v[24:27]
	v_mfma_f32_16x16x32_bf16 v[20:23], v[132:135], v[192:195], v[20:23]
	v_mfma_f32_16x16x32_bf16 v[8:11], v[150:153], v[192:195], v[8:11]

	s_barrier
	s_add_u32 s18, s18, 0x160080
	s_addc_u32 s19, s19, 0
	s_add_i32 s20, s20, s25
	s_mov_b32 m0, s20
	s_nop 0

	global_load_lds_dwordx4 v140, s[18:19]
	s_add_i32 m0, s20, 0x2000
	s_nop 0

	global_load_lds_dwordx4 v142, s[18:19]
	s_waitcnt vmcnt(6)
	s_barrier

	v_mfma_f32_16x16x32_bf16 v[48:51], v[196:199], v[154:157], v[48:51]
	v_mfma_f32_16x16x32_bf16 v[44:47], v[204:207], v[154:157], v[44:47]
	v_mfma_f32_16x16x32_bf16 v[32:35], v[196:199], v[172:175], v[32:35]
	v_mfma_f32_16x16x32_bf16 v[28:31], v[204:207], v[172:175], v[28:31]
	v_mfma_f32_16x16x32_bf16 v[16:19], v[196:199], v[180:183], v[16:19]
	v_mfma_f32_16x16x32_bf16 v[12:15], v[204:207], v[180:183], v[12:15]
	v_mfma_f32_16x16x32_bf16 v[4:7], v[196:199], v[188:191], v[4:7]
	v_mfma_f32_16x16x32_bf16 v[0:3], v[204:207], v[188:191], v[0:3]
	v_mfma_f32_16x16x32_bf16 v[48:51], v[200:203], v[162:165], v[48:51]
	v_mfma_f32_16x16x32_bf16 v[44:47], v[212:215], v[162:165], v[44:47]
	v_mfma_f32_16x16x32_bf16 v[32:35], v[200:203], v[176:179], v[32:35]
	v_mfma_f32_16x16x32_bf16 v[28:31], v[212:215], v[176:179], v[28:31]
	v_mfma_f32_16x16x32_bf16 v[16:19], v[200:203], v[184:187], v[16:19]
	v_mfma_f32_16x16x32_bf16 v[12:15], v[212:215], v[184:187], v[12:15]
	v_mfma_f32_16x16x32_bf16 v[4:7], v[200:203], v[192:195], v[4:7]
	v_mfma_f32_16x16x32_bf16 v[0:3], v[212:215], v[192:195], v[0:3]

	s_add_u32 s16, s16, 0x100
	s_addc_u32 s17, s17, 0
	s_add_u32 s52, s52, 0x100
	s_addc_u32 s53, s53, 0
	s_cmp_ge_i32 s54, s51
	s_mov_b32 s18, s54
	s_barrier
	s_cbranch_scc0 .LBB0_1258
	v_mov_b32_e32 v128, v210
	v_mov_b32_e32 v129, v169
	s_mov_b64 s[16:17], -1
	v_lshl_add_u32 v128, v128, 4, v129
	v_ashrrev_i32_e32 v150, 2, v128
	v_and_b32_e32 v129, 3, v129
	v_and_b32_e32 v128, -4, v128
	v_lshl_add_u32 v162, v129, 6, v128
	s_cmp_lt_i32 s2, 0
	v_lshlrev_b32_e32 v144, 4, v129
	s_cbranch_scc0 .LBB0_1261
	s_lshl_b32 s13, s50, 8
	s_add_i32 s13, s13, s30
	v_add_u32_e32 v128, s13, v150
	v_ashrrev_i32_e32 v129, 31, v128
	v_readlane_b32 s52, v254, 22
	v_lshlrev_b64 v[128:129], 13, v[128:129]
	v_readlane_b32 s66, v254, 36
	v_readlane_b32 s67, v254, 37
	s_lshl_b32 s16, s49, 8
	s_ashr_i32 s17, s16, 31
	v_lshl_add_u64 v[128:129], s[66:67], 0, v[128:129]
	v_lshl_add_u64 v[128:129], s[16:17], 2, v[128:129]
	s_lshl_b32 s16, s31, 2
	s_mov_b32 s17, s3
	v_lshl_add_u64 v[128:129], v[128:129], 0, s[16:17]
	v_lshl_add_u64 v[152:153], v[128:129], 0, v[144:145]
	global_load_dwordx4 v[164:167], v[152:153], off
	global_load_dwordx4 v[172:175], v[152:153], off offset:64
	global_load_dwordx4 v[176:179], v[152:153], off offset:512
	global_load_dwordx4 v[180:183], v[152:153], off offset:576
	v_add_co_u32_e32 v136, vcc, s37, v152
	ds_bpermute_b32 v138, v162, v124
	s_nop 0
	v_addc_co_u32_e32 v137, vcc, 0, v153, vcc
	global_load_dwordx4 v[184:187], v[136:137], off
	global_load_dwordx4 v[188:191], v[136:137], off offset:64
	global_load_dwordx4 v[192:195], v[136:137], off offset:512
	global_load_dwordx4 v[132:135], v[136:137], off offset:576
	v_add_co_u32_e32 v208, vcc, s38, v152
	ds_bpermute_b32 v139, v162, v125
	s_nop 0
	v_addc_co_u32_e32 v209, vcc, 0, v153, vcc
	global_load_dwordx4 v[196:199], v[208:209], off
	global_load_dwordx4 v[200:203], v[208:209], off offset:64
	global_load_dwordx4 v[204:207], v[208:209], off offset:512
	global_load_dwordx4 v[212:215], v[208:209], off offset:576
	v_add_co_u32_e32 v154, vcc, s39, v152
	ds_bpermute_b32 v156, v162, v126
	s_nop 0
	v_addc_co_u32_e32 v155, vcc, 0, v153, vcc
	global_load_dwordx4 v[216:219], v[154:155], off
	global_load_dwordx4 v[220:223], v[154:155], off offset:64
	global_load_dwordx4 v[224:227], v[154:155], off offset:512
	global_load_dwordx4 v[128:131], v[154:155], off offset:576
	ds_bpermute_b32 v157, v162, v127
	ds_bpermute_b32 v228, v162, v120
	ds_bpermute_b32 v229, v162, v121
	ds_bpermute_b32 v230, v162, v122
	ds_bpermute_b32 v231, v162, v123
	ds_bpermute_b32 v232, v162, v112
	ds_bpermute_b32 v233, v162, v113
	ds_bpermute_b32 v234, v162, v114
	ds_bpermute_b32 v235, v162, v115
	ds_bpermute_b32 v236, v162, v108
	ds_bpermute_b32 v237, v162, v109
	ds_bpermute_b32 v238, v162, v110
	ds_bpermute_b32 v239, v162, v111
	ds_bpermute_b32 v240, v162, v116
	ds_bpermute_b32 v241, v162, v117
	ds_bpermute_b32 v242, v162, v118
	ds_bpermute_b32 v243, v162, v119
	ds_bpermute_b32 v244, v162, v104
	ds_bpermute_b32 v245, v162, v105
	ds_bpermute_b32 v246, v162, v106
	ds_bpermute_b32 v247, v162, v107
	ds_bpermute_b32 v248, v162, v100
	ds_bpermute_b32 v249, v162, v101
	ds_bpermute_b32 v250, v162, v102
	ds_bpermute_b32 v251, v162, v103
	ds_bpermute_b32 v252, v162, v94
	ds_bpermute_b32 v253, v162, v95
	v_readlane_b32 s53, v254, 23
	v_readlane_b32 s54, v254, 24
	v_readlane_b32 s55, v254, 25
	v_readlane_b32 s56, v254, 26
	v_readlane_b32 s57, v254, 27
	v_readlane_b32 s58, v254, 28
	v_readlane_b32 s59, v254, 29
	v_readlane_b32 s60, v254, 30
	v_readlane_b32 s61, v254, 31
	v_readlane_b32 s62, v254, 32
	v_readlane_b32 s63, v254, 33
	v_readlane_b32 s64, v254, 34
	v_readlane_b32 s65, v254, 35
	s_mov_b64 s[16:17], 0
	s_waitcnt vmcnt(0) lgkmcnt(0)
	v_pk_add_f32 v[164:165], v[164:165], v[138:139]
	ds_bpermute_b32 v138, v162, v92
	ds_bpermute_b32 v139, v162, v93
	v_pk_add_f32 v[166:167], v[166:167], v[156:157]
	v_pk_add_f32 v[172:173], v[172:173], v[228:229]
	v_pk_add_f32 v[174:175], v[174:175], v[230:231]
	v_pk_add_f32 v[178:179], v[178:179], v[234:235]
	v_pk_add_f32 v[176:177], v[176:177], v[232:233]
	v_pk_add_f32 v[182:183], v[182:183], v[238:239]
	v_pk_add_f32 v[180:181], v[180:181], v[236:237]
	global_store_dwordx4 v[152:153], v[164:167], off
	global_store_dwordx4 v[152:153], v[172:175], off offset:64
	global_store_dwordx4 v[152:153], v[176:179], off offset:512
	global_store_dwordx4 v[152:153], v[180:183], off offset:576
	v_pk_add_f32 v[166:167], v[186:187], v[242:243]
	v_pk_add_f32 v[164:165], v[184:185], v[240:241]
	v_pk_add_f32 v[172:173], v[188:189], v[244:245]
	v_add_co_u32_e32 v156, vcc, s40, v152
	v_pk_add_f32 v[174:175], v[190:191], v[246:247]
	v_pk_add_f32 v[178:179], v[194:195], v[250:251]
	v_pk_add_f32 v[176:177], v[192:193], v[248:249]
	global_store_dwordx4 v[136:137], v[164:167], off
	global_store_dwordx4 v[136:137], v[172:175], off offset:64
	global_store_dwordx4 v[136:137], v[176:179], off offset:512
	v_addc_co_u32_e32 v157, vcc, 0, v153, vcc
	ds_bpermute_b32 v172, v162, v98
	ds_bpermute_b32 v173, v162, v99
	v_pk_add_f32 v[134:135], v[134:135], v[252:253]
	global_load_dwordx4 v[164:167], v[156:157], off
	s_waitcnt lgkmcnt(2)
	v_pk_add_f32 v[132:133], v[132:133], v[138:139]
	global_store_dwordx4 v[136:137], v[132:135], off offset:576
	ds_bpermute_b32 v132, v162, v96
	ds_bpermute_b32 v133, v162, v97
	ds_bpermute_b32 v136, v162, v90
	ds_bpermute_b32 v137, v162, v91
	ds_bpermute_b32 v138, v162, v88
	ds_bpermute_b32 v139, v162, v89
	s_waitcnt lgkmcnt(6)
	v_pk_add_f32 v[134:135], v[198:199], v[172:173]
	global_load_dwordx4 v[172:175], v[156:157], off offset:64
	s_waitcnt lgkmcnt(4)
	v_pk_add_f32 v[132:133], v[196:197], v[132:133]
	global_store_dwordx4 v[208:209], v[132:135], off
	ds_bpermute_b32 v180, v162, v76
	ds_bpermute_b32 v182, v162, v78
	s_waitcnt lgkmcnt(4)
	v_pk_add_f32 v[134:135], v[202:203], v[136:137]
	ds_bpermute_b32 v136, v162, v86
	ds_bpermute_b32 v137, v162, v87
	s_waitcnt lgkmcnt(4)
	v_pk_add_f32 v[132:133], v[200:201], v[138:139]
	ds_bpermute_b32 v138, v162, v84
	ds_bpermute_b32 v139, v162, v85
	global_store_dwordx4 v[208:209], v[132:135], off offset:64
	global_load_dwordx4 v[132:135], v[156:157], off offset:512
	s_waitcnt lgkmcnt(2)
	v_pk_add_f32 v[178:179], v[206:207], v[136:137]
	ds_bpermute_b32 v183, v162, v79
	s_waitcnt lgkmcnt(1)
	v_pk_add_f32 v[176:177], v[204:205], v[138:139]
	global_load_dwordx4 v[136:139], v[156:157], off offset:576
	ds_bpermute_b32 v181, v162, v77
	global_store_dwordx4 v[208:209], v[176:179], off offset:512
	v_add_co_u32_e32 v204, vcc, s41, v152
	s_waitcnt lgkmcnt(1)
	v_pk_add_f32 v[178:179], v[214:215], v[182:183]
	s_waitcnt lgkmcnt(0)
	v_pk_add_f32 v[176:177], v[212:213], v[180:181]
	ds_bpermute_b32 v180, v162, v80
	ds_bpermute_b32 v181, v162, v81
	ds_bpermute_b32 v182, v162, v82
	ds_bpermute_b32 v183, v162, v83
	v_addc_co_u32_e32 v205, vcc, 0, v153, vcc
	global_store_dwordx4 v[208:209], v[176:179], off offset:576
	global_load_dwordx4 v[176:179], v[204:205], off
	s_waitcnt lgkmcnt(0)
	v_pk_add_f32 v[182:183], v[218:219], v[182:183]
	global_load_dwordx4 v[184:187], v[204:205], off offset:64
	v_pk_add_f32 v[180:181], v[216:217], v[180:181]
	ds_bpermute_b32 v188, v162, v74
	ds_bpermute_b32 v189, v162, v75
	global_store_dwordx4 v[154:155], v[180:183], off
	ds_bpermute_b32 v180, v162, v72
	ds_bpermute_b32 v181, v162, v73
	ds_bpermute_b32 v192, v162, v68
	s_waitcnt lgkmcnt(3)
	v_pk_add_f32 v[182:183], v[222:223], v[188:189]
	global_load_dwordx4 v[188:191], v[204:205], off offset:512
	ds_bpermute_b32 v193, v162, v69
	s_waitcnt lgkmcnt(2)
	v_pk_add_f32 v[180:181], v[220:221], v[180:181]
	ds_bpermute_b32 v194, v162, v70
	ds_bpermute_b32 v195, v162, v71
	global_store_dwordx4 v[154:155], v[180:183], off offset:64
	global_load_dwordx4 v[180:183], v[204:205], off offset:576
	ds_bpermute_b32 v200, v162, v64
	ds_bpermute_b32 v196, v162, v66
	ds_bpermute_b32 v197, v162, v67
	ds_bpermute_b32 v201, v162, v65
	v_add_co_u32_e32 v206, vcc, s42, v152
	s_waitcnt lgkmcnt(4)
	v_pk_add_f32 v[194:195], v[226:227], v[194:195]
	v_pk_add_f32 v[192:193], v[224:225], v[192:193]
	v_addc_co_u32_e32 v207, vcc, 0, v153, vcc
	global_store_dwordx4 v[154:155], v[192:195], off offset:512
	global_load_dwordx4 v[192:195], v[206:207], off
	s_waitcnt lgkmcnt(1)
	v_pk_add_f32 v[130:131], v[130:131], v[196:197]
	s_waitcnt lgkmcnt(0)
	v_pk_add_f32 v[128:129], v[128:129], v[200:201]
	global_load_dwordx4 v[196:199], v[206:207], off offset:64
	ds_bpermute_b32 v202, v162, v62
	ds_bpermute_b32 v203, v162, v63
	global_store_dwordx4 v[154:155], v[128:131], off offset:576
	ds_bpermute_b32 v128, v162, v60
	ds_bpermute_b32 v129, v162, v61
	ds_bpermute_b32 v208, v162, v58
	ds_bpermute_b32 v209, v162, v59
	s_waitcnt vmcnt(18) lgkmcnt(4)
	v_pk_add_f32 v[130:131], v[166:167], v[202:203]
	ds_bpermute_b32 v154, v162, v56
	global_load_dwordx4 v[200:203], v[206:207], off offset:512
	ds_bpermute_b32 v155, v162, v57
	s_waitcnt lgkmcnt(4)
	v_pk_add_f32 v[128:129], v[164:165], v[128:129]
	global_load_dwordx4 v[164:167], v[206:207], off offset:576
	ds_bpermute_b32 v212, v162, v44
	global_store_dwordx4 v[156:157], v[128:131], off
	ds_bpermute_b32 v214, v162, v46
	ds_bpermute_b32 v215, v162, v47
	s_waitcnt vmcnt(19) lgkmcnt(5)
	v_pk_add_f32 v[130:131], v[174:175], v[208:209]
	v_add_co_u32_e32 v208, vcc, s43, v152
	s_waitcnt lgkmcnt(3)
	v_pk_add_f32 v[128:129], v[172:173], v[154:155]
	v_addc_co_u32_e32 v209, vcc, 0, v153, vcc
	global_store_dwordx4 v[156:157], v[128:131], off offset:64
	ds_bpermute_b32 v172, v162, v48
	ds_bpermute_b32 v173, v162, v49
	global_load_dwordx4 v[128:131], v[208:209], off
	global_load_dwordx4 v[152:155], v[208:209], off offset:64
	ds_bpermute_b32 v174, v162, v50
	ds_bpermute_b32 v175, v162, v51
	ds_bpermute_b32 v213, v162, v45
	s_waitcnt vmcnt(19) lgkmcnt(3)
	v_pk_add_f32 v[132:133], v[132:133], v[172:173]
	ds_bpermute_b32 v172, v162, v54
	ds_bpermute_b32 v173, v162, v55
	s_waitcnt lgkmcnt(3)
	v_pk_add_f32 v[134:135], v[134:135], v[174:175]
	global_store_dwordx4 v[156:157], v[132:135], off offset:512
	s_waitcnt vmcnt(16) lgkmcnt(0)
	v_pk_add_f32 v[174:175], v[178:179], v[172:173]
	v_pk_add_f32 v[134:135], v[138:139], v[214:215]
	v_pk_add_f32 v[132:133], v[136:137], v[212:213]
	global_store_dwordx4 v[156:157], v[132:135], off offset:576
	global_load_dwordx4 v[132:135], v[208:209], off offset:512
	ds_bpermute_b32 v156, v162, v52
	global_load_dwordx4 v[136:139], v[208:209], off offset:576
	ds_bpermute_b32 v157, v162, v53
	ds_bpermute_b32 v212, v162, v40
	ds_bpermute_b32 v214, v162, v42
	ds_bpermute_b32 v215, v162, v43
	ds_bpermute_b32 v213, v162, v41
	s_waitcnt lgkmcnt(4)
	v_pk_add_f32 v[172:173], v[176:177], v[156:157]
	global_store_dwordx4 v[204:205], v[172:175], off
	ds_bpermute_b32 v156, v162, v32
	ds_bpermute_b32 v157, v162, v33
	s_waitcnt vmcnt(19) lgkmcnt(3)
	v_pk_add_f32 v[174:175], v[186:187], v[214:215]
	s_waitcnt lgkmcnt(2)
	v_pk_add_f32 v[172:173], v[184:185], v[212:213]
	global_store_dwordx4 v[204:205], v[172:175], off offset:64
	ds_bpermute_b32 v172, v162, v34
	ds_bpermute_b32 v173, v162, v35
	ds_bpermute_b32 v176, v162, v28
	ds_bpermute_b32 v178, v162, v30
	ds_bpermute_b32 v179, v162, v31
	ds_bpermute_b32 v177, v162, v29
	s_waitcnt vmcnt(18) lgkmcnt(4)
	v_pk_add_f32 v[174:175], v[190:191], v[172:173]
	v_pk_add_f32 v[172:173], v[188:189], v[156:157]
	global_store_dwordx4 v[204:205], v[172:175], off offset:512
	ds_bpermute_b32 v156, v162, v36
	ds_bpermute_b32 v157, v162, v37
	s_waitcnt vmcnt(17) lgkmcnt(3)
	v_pk_add_f32 v[174:175], v[182:183], v[178:179]
	s_waitcnt lgkmcnt(2)
	v_pk_add_f32 v[172:173], v[180:181], v[176:177]
	global_store_dwordx4 v[204:205], v[172:175], off offset:576
	ds_bpermute_b32 v172, v162, v38
	ds_bpermute_b32 v173, v162, v39
	ds_bpermute_b32 v176, v162, v24
	ds_bpermute_b32 v178, v162, v26
	ds_bpermute_b32 v179, v162, v27
	ds_bpermute_b32 v177, v162, v25
	s_waitcnt vmcnt(16) lgkmcnt(4)
	v_pk_add_f32 v[174:175], v[194:195], v[172:173]
	v_pk_add_f32 v[172:173], v[192:193], v[156:157]
	global_store_dwordx4 v[206:207], v[172:175], off
	ds_bpermute_b32 v156, v162, v16
	ds_bpermute_b32 v157, v162, v17
	s_waitcnt vmcnt(16) lgkmcnt(3)
	v_pk_add_f32 v[174:175], v[198:199], v[178:179]
	s_waitcnt lgkmcnt(2)
	v_pk_add_f32 v[172:173], v[196:197], v[176:177]
	ds_bpermute_b32 v176, v162, v12
	ds_bpermute_b32 v178, v162, v14
	ds_bpermute_b32 v179, v162, v15
	ds_bpermute_b32 v177, v162, v13
	global_store_dwordx4 v[206:207], v[172:175], off offset:64
	ds_bpermute_b32 v172, v162, v18
	ds_bpermute_b32 v173, v162, v19
	s_waitcnt vmcnt(14) lgkmcnt(3)
	v_pk_add_f32 v[166:167], v[166:167], v[178:179]
	s_waitcnt lgkmcnt(2)
	v_pk_add_f32 v[164:165], v[164:165], v[176:177]
	global_store_dwordx4 v[206:207], v[164:167], off offset:576
	ds_bpermute_b32 v164, v162, v22
	s_waitcnt lgkmcnt(1)
	v_pk_add_f32 v[174:175], v[202:203], v[172:173]
	v_pk_add_f32 v[172:173], v[200:201], v[156:157]
	ds_bpermute_b32 v156, v162, v20
	ds_bpermute_b32 v157, v162, v21
	ds_bpermute_b32 v165, v162, v23
	global_store_dwordx4 v[206:207], v[172:175], off offset:512
	ds_bpermute_b32 v166, v162, v8
	ds_bpermute_b32 v172, v162, v10
	ds_bpermute_b32 v173, v162, v11
	ds_bpermute_b32 v167, v162, v9
	s_waitcnt vmcnt(13) lgkmcnt(4)
	v_pk_add_f32 v[130:131], v[130:131], v[164:165]
	v_pk_add_f32 v[128:129], v[128:129], v[156:157]
	global_store_dwordx4 v[208:209], v[128:131], off
	s_waitcnt vmcnt(13) lgkmcnt(1)
	s_nop 0
	v_pk_add_f32 v[130:131], v[154:155], v[172:173]
	s_waitcnt lgkmcnt(0)
	v_pk_add_f32 v[128:129], v[152:153], v[166:167]
	global_store_dwordx4 v[208:209], v[128:131], off offset:64
	ds_bpermute_b32 v128, v162, v4
	ds_bpermute_b32 v129, v162, v5
	ds_bpermute_b32 v130, v162, v6
	ds_bpermute_b32 v131, v162, v7
	ds_bpermute_b32 v152, v162, v0
	ds_bpermute_b32 v154, v162, v2
	ds_bpermute_b32 v155, v162, v3
	ds_bpermute_b32 v153, v162, v1
	s_waitcnt vmcnt(11) lgkmcnt(4)
	v_pk_add_f32 v[130:131], v[134:135], v[130:131]
	v_pk_add_f32 v[128:129], v[132:133], v[128:129]
	global_store_dwordx4 v[208:209], v[128:131], off offset:512
	s_waitcnt vmcnt(11) lgkmcnt(1)
	s_nop 0
	v_pk_add_f32 v[130:131], v[138:139], v[154:155]
	s_waitcnt lgkmcnt(0)
	v_pk_add_f32 v[128:129], v[136:137], v[152:153]
	global_store_dwordx4 v[208:209], v[128:131], off offset:576
